# kzz order + first K-loop iteration peeled (srcC=0), accumulator zeroing moves removed
# speedup vs baseline: 1.0210x; 1.0050x over previous
; #define PG8_STAGE(bufoff, gbase, voff) do { _Pragma("unroll") for (int _i = 0; _i < 2; ++_i) \
;         __builtin_amdgcn_global_load_lds((const unsigned*)((const char*)(gbase) + (voff)[_i]), (PG8_LAS unsigned*)(lds + (bufoff) + ldsw + _i * 8192), 16, 0, 0); } while (0)
; #define PG8_LDA(dst, b, h) do { _Pragma("unroll") for (int m = 0; m < 4; ++m) _Pragma("unroll") for (int k = 0; k < 2; ++k) dst[m][k] = *(const PG8_LAS bf16x8*)(lds + PG8_SA(b, h) + aoff + m * 2048 + k * 1024); } while (0)
; #define PG8_LDB(dst, b, h) do { _Pragma("unroll") for (int n = 0; n < 2; ++n) _Pragma("unroll") for (int k = 0; k < 2; ++k) dst[n][k] = *(const PG8_LAS bf16x8*)(lds + PG8_SB(b, h) + boff + n * 2048 + k * 1024); } while (0)
; #define PG8_WAIT_V(n) asm volatile("s_waitcnt vmcnt(" #n ")" ::: "memory")
; #define PG8_WAIT_L(n) asm volatile("s_waitcnt lgkmcnt(" #n ")" ::: "memory")
; #define PG8_BAR __builtin_amdgcn_s_barrier()
; #define PG8_SCHED __builtin_amdgcn_sched_barrier(0)
; template <class Epi, class Sched, bool ALIGN_EPI = false, bool SP2 = false>
; __device__ __forceinline__ void gemm_phase(PG8_LAS unsigned char* lds, const Gemm g, const Sched& S, const Epi& E) {
;     ...
;         const bool has_next = S.next(ui + 1, nxt);
;         const char* nA = has_next ? (const char*)g.A + (size_t)nxt.pm * tstep : cA; const char* nB = has_next ? (const char*)g.Bt + (size_t)nxt.pn * tstep : cB;
;         for (int t = 0; t < nt; t += 2) {
;             const bool last = (t == nt - 2);
;             const char* a1 = cA + (size_t)(t + 1) * kstep;
;             const char* a2 = last ? nA : cA + (size_t)(t + 2) * kstep; const char* b2 = last ? nB : cB + (size_t)(t + 2) * kstep;
;             const char* a3 = a2 + kstep; const char* b3 = b2 + kstep;
;             if (last && has_next) S.a_ready(nxt);
;             if constexpr (Epi::MID) { if (t == nt / 2) E.mid(acc, cur, wr, wc, fr, fq); }
;             if constexpr (SP2) {
;             PG8_LDB(B0, 0, 0); PG8_LDB(B1, 0, 1); PG8_SCHED; PG8_LDA(At, 0, 0); PG8_STAGE(PG8_SA(1, 1), a1 + hstep, voffA);
;             PG8_WAIT_V(8); PG8_WAIT_L(0); PG8_BAR; PG8_MMA(0, 0, At, B0); PG8_MMA(0, 1, At, B1); PG8_BAR; PG8_SCHED;
;             PG8_LDA(At, 0, 1); PG8_STAGE(PG8_SB(0, 0), b2, voffB); PG8_STAGE(PG8_SB(0, 1), b2 + hstep, voffB); PG8_STAGE(PG8_SA(0, 0), a2, voffA);
.LBB0_372:
	s_ashr_i32 s21, s20, 31
	s_lshl_b64 s[22:23], s[20:21], 20
	s_add_u32 s22, s8, s22
	s_addc_u32 s23, s9, s23
	s_and_b64 s[24:25], s[2:3], exec
	s_cselect_b32 s5, s23, s29
	s_cselect_b32 s11, s22, s28
	s_ashr_i32 s19, s18, 31
	s_lshl_b64 s[24:25], s[18:19], 20
	s_add_u32 s24, s35, s24
	s_addc_u32 s25, s36, s25
	s_and_b64 s[30:31], s[2:3], exec
	s_cselect_b32 s19, s25, s27
	s_cselect_b32 s21, s24, s26
	s_add_u32 s53, s26, 0x100
	s_addc_u32 s54, s27, 0
	s_add_u32 s26, s28, 0x80080
	s_addc_u32 s27, s29, 0
	s_mov_b32 s55, -2
	s_waitcnt vmcnt(0)
	s_add_u32 s28, s26, 0xfff80080
	s_addc_u32 s29, s27, -1
	s_add_i32 s33, 0, 0x10000
	s_cmp_eq_u32 s55, 28
	s_cselect_b32 s31, s5, s29
	s_cselect_b32 s30, s11, s28
	v_add_u32_e32 v161, s33, v155
	s_cselect_b32 s29, s19, s54
	s_cselect_b32 s28, s21, s53
	s_add_i32 s58, 0, 0x14000
	ds_read_b128 v[142:145], v161
	ds_read_b128 v[146:149], v161 offset:1024
	ds_read_b128 v[150:153], v161 offset:2048
	ds_read_b128 v[162:165], v161 offset:3072
	v_add_u32_e32 v161, s58, v155
	ds_read_b128 v[166:169], v161
	ds_read_b128 v[170:173], v161 offset:1024
	ds_read_b128 v[174:177], v161 offset:2048
	ds_read_b128 v[178:181], v161 offset:3072
	v_lshl_add_u64 v[202:203], s[26:27], 0, v[140:141]
	s_add_i32 m0, s41, 0xc000
	ds_read_b128 v[182:185], v160
	ds_read_b128 v[186:189], v160 offset:1024
	ds_read_b128 v[190:193], v160 offset:2048
	ds_read_b128 v[194:197], v160 offset:3072
	ds_read_b128 v[198:201], v160 offset:4096
	ds_read_b128 v[206:209], v160 offset:5120
	ds_read_b128 v[210:213], v160 offset:6144
	ds_read_b128 v[214:217], v160 offset:7168
	global_load_lds_dwordx4 v140, s[26:27]
	v_lshl_add_u64 v[202:203], s[26:27], 0, v[138:139]
	s_add_i32 m0, s41, 0xe000
	s_nop 0
	global_load_lds_dwordx4 v138, s[26:27]
	s_waitcnt vmcnt(8)
	s_waitcnt lgkmcnt(0)
	s_barrier
	s_setprio 1
	s_waitcnt lgkmcnt(0)
	v_mfma_f32_16x16x32_bf16 v[130:133], v[142:145], v[182:185], 0
	v_mfma_f32_16x16x32_bf16 v[130:133], v[146:149], v[186:189], v[130:133]
	v_mfma_f32_16x16x32_bf16 v[126:129], v[162:165], v[186:189], 0
	v_mfma_f32_16x16x32_bf16 v[126:129], v[150:153], v[182:185], v[126:129]
	v_mfma_f32_16x16x32_bf16 v[110:113], v[150:153], v[190:193], 0
	v_mfma_f32_16x16x32_bf16 v[110:113], v[162:165], v[194:197], v[110:113]
	v_mfma_f32_16x16x32_bf16 v[114:117], v[146:149], v[194:197], 0
	v_mfma_f32_16x16x32_bf16 v[114:117], v[142:145], v[190:193], v[114:117]
	v_mfma_f32_16x16x32_bf16 v[98:101], v[142:145], v[198:201], 0
	v_mfma_f32_16x16x32_bf16 v[98:101], v[146:149], v[206:209], v[98:101]
	v_mfma_f32_16x16x32_bf16 v[94:97], v[162:165], v[206:209], 0
	v_mfma_f32_16x16x32_bf16 v[94:97], v[150:153], v[198:201], v[94:97]
	v_mfma_f32_16x16x32_bf16 v[78:81], v[150:153], v[210:213], 0
	v_mfma_f32_16x16x32_bf16 v[78:81], v[162:165], v[214:217], v[78:81]
	v_mfma_f32_16x16x32_bf16 v[82:85], v[146:149], v[214:217], 0
	v_mfma_f32_16x16x32_bf16 v[82:85], v[142:145], v[210:213], v[82:85]
	s_setprio 0
	s_setprio 1
	v_mfma_f32_16x16x32_bf16 v[122:125], v[166:169], v[182:185], 0
	v_mfma_f32_16x16x32_bf16 v[122:125], v[170:173], v[186:189], v[122:125]
	v_mfma_f32_16x16x32_bf16 v[118:121], v[178:181], v[186:189], 0
	v_mfma_f32_16x16x32_bf16 v[118:121], v[174:177], v[182:185], v[118:121]
	v_mfma_f32_16x16x32_bf16 v[102:105], v[174:177], v[190:193], 0
	v_mfma_f32_16x16x32_bf16 v[102:105], v[178:181], v[194:197], v[102:105]
	v_mfma_f32_16x16x32_bf16 v[106:109], v[170:173], v[194:197], 0
	v_mfma_f32_16x16x32_bf16 v[106:109], v[166:169], v[190:193], v[106:109]
	v_mfma_f32_16x16x32_bf16 v[90:93], v[166:169], v[198:201], 0
	v_mfma_f32_16x16x32_bf16 v[90:93], v[170:173], v[206:209], v[90:93]
	v_mfma_f32_16x16x32_bf16 v[86:89], v[178:181], v[206:209], 0
	v_mfma_f32_16x16x32_bf16 v[86:89], v[174:177], v[198:201], v[86:89]
	v_mfma_f32_16x16x32_bf16 v[70:73], v[174:177], v[210:213], 0
	v_mfma_f32_16x16x32_bf16 v[70:73], v[178:181], v[214:217], v[70:73]
	v_mfma_f32_16x16x32_bf16 v[74:77], v[170:173], v[214:217], 0
	v_mfma_f32_16x16x32_bf16 v[74:77], v[166:169], v[210:213], v[74:77]
	s_setprio 0
	s_barrier
	s_add_i32 s33, s33, s39
	v_lshl_add_u64 v[202:203], s[28:29], 0, v[0:1]
	s_mov_b32 m0, s33
	ds_read_b128 v[182:185], v160 offset:16384
	ds_read_b128 v[186:189], v160 offset:17408
	ds_read_b128 v[190:193], v160 offset:18432
	ds_read_b128 v[194:197], v160 offset:19456
	ds_read_b128 v[198:201], v160 offset:20480
	ds_read_b128 v[206:209], v160 offset:21504
	ds_read_b128 v[210:213], v160 offset:22528
	ds_read_b128 v[214:217], v160 offset:23552
	global_load_lds_dwordx4 v0, s[28:29]
	s_add_i32 m0, s33, 0x2000
	s_add_u32 s56, s28, 0x80000
	v_lshl_add_u64 v[218:219], s[28:29], 0, v[14:15]
	s_addc_u32 s57, s29, 0
	s_add_i32 s33, s58, s39
	global_load_lds_dwordx4 v14, s[28:29]
	v_lshl_add_u64 v[220:221], s[56:57], 0, v[0:1]
	s_mov_b32 m0, s33
	v_lshl_add_u64 v[222:223], s[30:31], 0, v[134:135]
	global_load_lds_dwordx4 v0, s[56:57]
	v_lshl_add_u64 v[220:221], s[56:57], 0, v[14:15]
	s_add_i32 m0, s33, 0x2000
	s_nop 0
	global_load_lds_dwordx4 v14, s[56:57]
	v_lshl_add_u64 v[220:221], s[30:31], 0, v[136:137]
	s_mov_b32 m0, s41
	s_nop 0
	global_load_lds_dwordx4 v136, s[30:31]
	s_mov_b32 m0, s42
	s_nop 0
	global_load_lds_dwordx4 v134, s[30:31]
	s_waitcnt vmcnt(8)
	s_waitcnt lgkmcnt(0)
	s_barrier
; #define PG8_STAGE(bufoff, gbase, voff) do { _Pragma("unroll") for (int _i = 0; _i < 2; ++_i) \
;         __builtin_amdgcn_global_load_lds((const unsigned*)((const char*)(gbase) + (voff)[_i]), (PG8_LAS unsigned*)(lds + (bufoff) + ldsw + _i * 8192), 16, 0, 0); } while (0)
; #define PG8_LDA(dst, b, h) do { _Pragma("unroll") for (int m = 0; m < 4; ++m) _Pragma("unroll") for (int k = 0; k < 2; ++k) dst[m][k] = *(const PG8_LAS bf16x8*)(lds + PG8_SA(b, h) + aoff + m * 2048 + k * 1024); } while (0)
; #define PG8_LDB(dst, b, h) do { _Pragma("unroll") for (int n = 0; n < 2; ++n) _Pragma("unroll") for (int k = 0; k < 2; ++k) dst[n][k] = *(const PG8_LAS bf16x8*)(lds + PG8_SB(b, h) + boff + n * 2048 + k * 1024); } while (0)
; #define PG8_MMA(ai, bj, At, Bt) do { __builtin_amdgcn_s_setprio(1); _Pragma("unroll") for (int m = 0; m < 4; ++m) _Pragma("unroll") for (int n = 0; n < 2; ++n) _Pragma("unroll") for (int k = 0; k < 2; ++k) \
;         acc[ai][bj][m][n] = __builtin_amdgcn_mfma_f32_16x16x32_bf16(Bt[n][k], At[m][k], acc[ai][bj][m][n], 0, 0, 0); __builtin_amdgcn_s_setprio(0); } while (0)
; #define PG8_WAIT_V(n) asm volatile("s_waitcnt vmcnt(" #n ")" ::: "memory")
; #define PG8_WAIT_L(n) asm volatile("s_waitcnt lgkmcnt(" #n ")" ::: "memory")
; #define PG8_BAR __builtin_amdgcn_s_barrier()
; #define PG8_SCHED __builtin_amdgcn_sched_barrier(0)
; template <class Epi, class Sched, bool ALIGN_EPI = false, bool SP2 = false>
; __device__ __forceinline__ void gemm_phase(PG8_LAS unsigned char* lds, const Gemm g, const Sched& S, const Epi& E) {
;     ...
;             PG8_WAIT_V(8); PG8_WAIT_L(0); PG8_BAR; PG8_MMA(1, 0, At, B0); PG8_MMA(1, 1, At, B1); PG8_BAR; PG8_SCHED;
;             PG8_LDB(B0, 1, 0); PG8_LDB(B1, 1, 1); PG8_SCHED; PG8_LDA(At, 1, 0); PG8_STAGE(PG8_SA(0, 1), a2 + hstep, voffA);
;             PG8_WAIT_V(8); PG8_WAIT_L(0); PG8_BAR; PG8_MMA(0, 0, At, B0); PG8_MMA(0, 1, At, B1); PG8_BAR; PG8_SCHED;
	s_setprio 1
	s_waitcnt lgkmcnt(0)
	v_mfma_f32_16x16x32_bf16 v[66:69], v[142:145], v[182:185], 0
	v_mfma_f32_16x16x32_bf16 v[66:69], v[146:149], v[186:189], v[66:69]
	v_mfma_f32_16x16x32_bf16 v[62:65], v[162:165], v[186:189], 0
	v_mfma_f32_16x16x32_bf16 v[62:65], v[150:153], v[182:185], v[62:65]
	v_mfma_f32_16x16x32_bf16 v[46:49], v[150:153], v[190:193], 0
	v_mfma_f32_16x16x32_bf16 v[46:49], v[162:165], v[194:197], v[46:49]
	v_mfma_f32_16x16x32_bf16 v[50:53], v[146:149], v[194:197], 0
	v_mfma_f32_16x16x32_bf16 v[50:53], v[142:145], v[190:193], v[50:53]
	v_mfma_f32_16x16x32_bf16 v[34:37], v[142:145], v[198:201], 0
	v_mfma_f32_16x16x32_bf16 v[34:37], v[146:149], v[206:209], v[34:37]
	v_mfma_f32_16x16x32_bf16 v[30:33], v[162:165], v[206:209], 0
	v_mfma_f32_16x16x32_bf16 v[30:33], v[150:153], v[198:201], v[30:33]
	v_mfma_f32_16x16x32_bf16 v[10:13], v[150:153], v[210:213], 0
	v_mfma_f32_16x16x32_bf16 v[10:13], v[162:165], v[214:217], v[10:13]
	v_mfma_f32_16x16x32_bf16 v[18:21], v[146:149], v[214:217], 0
	v_mfma_f32_16x16x32_bf16 v[18:21], v[142:145], v[210:213], v[18:21]
	s_setprio 0
	s_setprio 1
	v_mfma_f32_16x16x32_bf16 v[58:61], v[166:169], v[182:185], 0
	v_mfma_f32_16x16x32_bf16 v[58:61], v[170:173], v[186:189], v[58:61]
	v_mfma_f32_16x16x32_bf16 v[54:57], v[178:181], v[186:189], 0
	v_mfma_f32_16x16x32_bf16 v[54:57], v[174:177], v[182:185], v[54:57]
	v_mfma_f32_16x16x32_bf16 v[38:41], v[174:177], v[190:193], 0
	v_mfma_f32_16x16x32_bf16 v[38:41], v[178:181], v[194:197], v[38:41]
	v_mfma_f32_16x16x32_bf16 v[42:45], v[170:173], v[194:197], 0
	v_mfma_f32_16x16x32_bf16 v[42:45], v[166:169], v[190:193], v[42:45]
	v_mfma_f32_16x16x32_bf16 v[26:29], v[166:169], v[198:201], 0
	v_mfma_f32_16x16x32_bf16 v[26:29], v[170:173], v[206:209], v[26:29]
	v_mfma_f32_16x16x32_bf16 v[22:25], v[178:181], v[206:209], 0
	v_mfma_f32_16x16x32_bf16 v[22:25], v[174:177], v[198:201], v[22:25]
	v_mfma_f32_16x16x32_bf16 v[2:5], v[174:177], v[210:213], 0
	v_mfma_f32_16x16x32_bf16 v[2:5], v[178:181], v[214:217], v[2:5]
	v_mfma_f32_16x16x32_bf16 v[6:9], v[170:173], v[214:217], 0
	v_mfma_f32_16x16x32_bf16 v[6:9], v[166:169], v[210:213], v[6:9]
	s_setprio 0
	s_barrier
	s_add_i32 s33, 0, 0x18000
	v_add_u32_e32 v161, s33, v155
	s_add_i32 s56, 0, 0x1c000
	ds_read_b128 v[142:145], v161
	ds_read_b128 v[146:149], v161 offset:1024
	ds_read_b128 v[150:153], v161 offset:2048
	ds_read_b128 v[162:165], v161 offset:3072
	v_add_u32_e32 v161, s56, v155
	ds_read_b128 v[166:169], v161
	ds_read_b128 v[170:173], v161 offset:1024
	ds_read_b128 v[174:177], v161 offset:2048
	ds_read_b128 v[178:181], v161 offset:3072
	s_add_u32 s30, s30, 0x80000
	s_addc_u32 s31, s31, 0
	s_mov_b32 m0, s43
	v_lshl_add_u64 v[224:225], s[30:31], 0, v[136:137]
	ds_read_b128 v[182:185], v160 offset:32768
	ds_read_b128 v[186:189], v160 offset:33792
	ds_read_b128 v[190:193], v160 offset:34816
	ds_read_b128 v[194:197], v160 offset:35840
	ds_read_b128 v[198:201], v160 offset:36864
	ds_read_b128 v[206:209], v160 offset:37888
	ds_read_b128 v[210:213], v160 offset:38912
	ds_read_b128 v[214:217], v160 offset:39936
	global_load_lds_dwordx4 v136, s[30:31]
	v_lshl_add_u64 v[224:225], s[30:31], 0, v[134:135]
	s_mov_b32 m0, s44
	s_nop 0
	global_load_lds_dwordx4 v134, s[30:31]
	s_waitcnt vmcnt(8)
	s_waitcnt lgkmcnt(0)
	s_barrier
	s_setprio 1
	s_waitcnt lgkmcnt(0)
	v_mfma_f32_16x16x32_bf16 v[130:133], v[142:145], v[182:185], v[130:133]
	v_mfma_f32_16x16x32_bf16 v[130:133], v[146:149], v[186:189], v[130:133]
	v_mfma_f32_16x16x32_bf16 v[126:129], v[162:165], v[186:189], v[126:129]
	v_mfma_f32_16x16x32_bf16 v[126:129], v[150:153], v[182:185], v[126:129]
	v_mfma_f32_16x16x32_bf16 v[110:113], v[150:153], v[190:193], v[110:113]
	v_mfma_f32_16x16x32_bf16 v[110:113], v[162:165], v[194:197], v[110:113]
	v_mfma_f32_16x16x32_bf16 v[114:117], v[146:149], v[194:197], v[114:117]
	v_mfma_f32_16x16x32_bf16 v[114:117], v[142:145], v[190:193], v[114:117]
	v_mfma_f32_16x16x32_bf16 v[98:101], v[142:145], v[198:201], v[98:101]
	v_mfma_f32_16x16x32_bf16 v[98:101], v[146:149], v[206:209], v[98:101]
	v_mfma_f32_16x16x32_bf16 v[94:97], v[162:165], v[206:209], v[94:97]
	v_mfma_f32_16x16x32_bf16 v[94:97], v[150:153], v[198:201], v[94:97]
	v_mfma_f32_16x16x32_bf16 v[78:81], v[150:153], v[210:213], v[78:81]
	v_mfma_f32_16x16x32_bf16 v[78:81], v[162:165], v[214:217], v[78:81]
	v_mfma_f32_16x16x32_bf16 v[82:85], v[146:149], v[214:217], v[82:85]
	v_mfma_f32_16x16x32_bf16 v[82:85], v[142:145], v[210:213], v[82:85]
	s_setprio 0
	s_setprio 1
	v_mfma_f32_16x16x32_bf16 v[122:125], v[166:169], v[182:185], v[122:125]
	v_mfma_f32_16x16x32_bf16 v[122:125], v[170:173], v[186:189], v[122:125]
	v_mfma_f32_16x16x32_bf16 v[118:121], v[178:181], v[186:189], v[118:121]
	v_mfma_f32_16x16x32_bf16 v[118:121], v[174:177], v[182:185], v[118:121]
	v_mfma_f32_16x16x32_bf16 v[102:105], v[174:177], v[190:193], v[102:105]
	v_mfma_f32_16x16x32_bf16 v[102:105], v[178:181], v[194:197], v[102:105]
	v_mfma_f32_16x16x32_bf16 v[106:109], v[170:173], v[194:197], v[106:109]
	v_mfma_f32_16x16x32_bf16 v[106:109], v[166:169], v[190:193], v[106:109]
	v_mfma_f32_16x16x32_bf16 v[90:93], v[166:169], v[198:201], v[90:93]
	v_mfma_f32_16x16x32_bf16 v[90:93], v[170:173], v[206:209], v[90:93]
	v_mfma_f32_16x16x32_bf16 v[86:89], v[178:181], v[206:209], v[86:89]
	v_mfma_f32_16x16x32_bf16 v[86:89], v[174:177], v[198:201], v[86:89]
	v_mfma_f32_16x16x32_bf16 v[70:73], v[174:177], v[210:213], v[70:73]
	v_mfma_f32_16x16x32_bf16 v[70:73], v[178:181], v[214:217], v[70:73]
	v_mfma_f32_16x16x32_bf16 v[74:77], v[170:173], v[214:217], v[74:77]
	v_mfma_f32_16x16x32_bf16 v[74:77], v[166:169], v[210:213], v[74:77]
	s_setprio 0
	s_barrier
; #define PG8_STAGE(bufoff, gbase, voff) do { _Pragma("unroll") for (int _i = 0; _i < 2; ++_i) \
;         __builtin_amdgcn_global_load_lds((const unsigned*)((const char*)(gbase) + (voff)[_i]), (PG8_LAS unsigned*)(lds + (bufoff) + ldsw + _i * 8192), 16, 0, 0); } while (0)
; #define PG8_LDA(dst, b, h) do { _Pragma("unroll") for (int m = 0; m < 4; ++m) _Pragma("unroll") for (int k = 0; k < 2; ++k) dst[m][k] = *(const PG8_LAS bf16x8*)(lds + PG8_SA(b, h) + aoff + m * 2048 + k * 1024); } while (0)
; #define PG8_MMA(ai, bj, At, Bt) do { __builtin_amdgcn_s_setprio(1); _Pragma("unroll") for (int m = 0; m < 4; ++m) _Pragma("unroll") for (int n = 0; n < 2; ++n) _Pragma("unroll") for (int k = 0; k < 2; ++k) \
;         acc[ai][bj][m][n] = __builtin_amdgcn_mfma_f32_16x16x32_bf16(Bt[n][k], At[m][k], acc[ai][bj][m][n], 0, 0, 0); __builtin_amdgcn_s_setprio(0); } while (0)
; #define PG8_WAIT_V(n) asm volatile("s_waitcnt vmcnt(" #n ")" ::: "memory")
; #define PG8_WAIT_L(n) asm volatile("s_waitcnt lgkmcnt(" #n ")" ::: "memory")
; #define PG8_BAR __builtin_amdgcn_s_barrier()
; #define PG8_SCHED __builtin_amdgcn_sched_barrier(0)
; template <class Epi, class Sched, bool ALIGN_EPI = false, bool SP2 = false>
; __device__ __forceinline__ void gemm_phase(PG8_LAS unsigned char* lds, const Gemm g, const Sched& S, const Epi& E) {
;     ...
;         for (int t = 0; t < nt; t += 2) {
;     ...
;             PG8_LDA(At, 1, 1); PG8_STAGE(PG8_SB(1, 0), b3, voffB); PG8_STAGE(PG8_SB(1, 1), b3 + hstep, voffB); PG8_STAGE(PG8_SA(1, 0), a3, voffA);
;             PG8_WAIT_V(8); PG8_WAIT_L(0); PG8_BAR; PG8_MMA(1, 0, At, B0); PG8_MMA(1, 1, At, B1); PG8_BAR; PG8_SCHED;
	s_add_i32 s30, s33, s39
	v_lshl_add_u64 v[202:203], v[202:203], 0, s[92:93]
	s_mov_b32 m0, s30
	ds_read_b128 v[182:185], v160 offset:49152
	ds_read_b128 v[186:189], v160 offset:50176
	ds_read_b128 v[190:193], v160 offset:51200
	ds_read_b128 v[194:197], v160 offset:52224
	ds_read_b128 v[198:201], v160 offset:53248
	ds_read_b128 v[206:209], v160 offset:54272
	ds_read_b128 v[210:213], v160 offset:55296
	ds_read_b128 v[214:217], v160 offset:56320
	global_load_lds_dwordx4 v[202:203], off
	s_add_i32 m0, s30, 0x2000
	s_add_u32 s28, s28, 0x80080
	v_lshl_add_u64 v[202:203], v[218:219], 0, s[92:93]
	s_addc_u32 s29, s29, 0
	s_add_i32 s30, s56, s39
	global_load_lds_dwordx4 v[202:203], off
	v_lshl_add_u64 v[202:203], s[28:29], 0, v[0:1]
	s_mov_b32 m0, s30
	s_nop 0
	global_load_lds_dwordx4 v0, s[28:29]
	v_lshl_add_u64 v[202:203], s[28:29], 0, v[14:15]
	s_add_i32 m0, s30, 0x2000
	s_nop 0
	global_load_lds_dwordx4 v14, s[28:29]
	v_lshl_add_u64 v[202:203], v[220:221], 0, s[92:93]
	s_mov_b32 m0, s46
	s_nop 0
	global_load_lds_dwordx4 v[202:203], off
	v_lshl_add_u64 v[202:203], v[222:223], 0, s[92:93]
	s_mov_b32 m0, s47
	s_nop 0
	global_load_lds_dwordx4 v[202:203], off
	s_waitcnt vmcnt(8)
	s_waitcnt lgkmcnt(0)
	s_barrier
	s_setprio 1
	s_waitcnt lgkmcnt(0)
	v_mfma_f32_16x16x32_bf16 v[66:69], v[142:145], v[182:185], v[66:69]
	v_mfma_f32_16x16x32_bf16 v[66:69], v[146:149], v[186:189], v[66:69]
	v_mfma_f32_16x16x32_bf16 v[62:65], v[162:165], v[186:189], v[62:65]
	v_mfma_f32_16x16x32_bf16 v[62:65], v[150:153], v[182:185], v[62:65]
	v_mfma_f32_16x16x32_bf16 v[46:49], v[150:153], v[190:193], v[46:49]
	v_mfma_f32_16x16x32_bf16 v[46:49], v[162:165], v[194:197], v[46:49]
	v_mfma_f32_16x16x32_bf16 v[50:53], v[146:149], v[194:197], v[50:53]
	v_mfma_f32_16x16x32_bf16 v[50:53], v[142:145], v[190:193], v[50:53]
	v_mfma_f32_16x16x32_bf16 v[34:37], v[142:145], v[198:201], v[34:37]
	v_mfma_f32_16x16x32_bf16 v[34:37], v[146:149], v[206:209], v[34:37]
	v_mfma_f32_16x16x32_bf16 v[30:33], v[162:165], v[206:209], v[30:33]
	v_mfma_f32_16x16x32_bf16 v[30:33], v[150:153], v[198:201], v[30:33]
	v_mfma_f32_16x16x32_bf16 v[10:13], v[150:153], v[210:213], v[10:13]
	v_mfma_f32_16x16x32_bf16 v[10:13], v[162:165], v[214:217], v[10:13]
	v_mfma_f32_16x16x32_bf16 v[18:21], v[146:149], v[214:217], v[18:21]
	v_mfma_f32_16x16x32_bf16 v[18:21], v[142:145], v[210:213], v[18:21]
	s_setprio 0
	s_setprio 1
	v_mfma_f32_16x16x32_bf16 v[58:61], v[166:169], v[182:185], v[58:61]
	v_mfma_f32_16x16x32_bf16 v[58:61], v[170:173], v[186:189], v[58:61]
	v_mfma_f32_16x16x32_bf16 v[54:57], v[178:181], v[186:189], v[54:57]
	v_mfma_f32_16x16x32_bf16 v[54:57], v[174:177], v[182:185], v[54:57]
	v_mfma_f32_16x16x32_bf16 v[38:41], v[174:177], v[190:193], v[38:41]
	v_mfma_f32_16x16x32_bf16 v[38:41], v[178:181], v[194:197], v[38:41]
	v_mfma_f32_16x16x32_bf16 v[42:45], v[170:173], v[194:197], v[42:45]
	v_mfma_f32_16x16x32_bf16 v[42:45], v[166:169], v[190:193], v[42:45]
	v_mfma_f32_16x16x32_bf16 v[26:29], v[166:169], v[198:201], v[26:29]
	v_mfma_f32_16x16x32_bf16 v[26:29], v[170:173], v[206:209], v[26:29]
	v_mfma_f32_16x16x32_bf16 v[22:25], v[178:181], v[206:209], v[22:25]
	v_mfma_f32_16x16x32_bf16 v[22:25], v[174:177], v[198:201], v[22:25]
	v_mfma_f32_16x16x32_bf16 v[2:5], v[174:177], v[210:213], v[2:5]
	v_mfma_f32_16x16x32_bf16 v[2:5], v[178:181], v[214:217], v[2:5]
	v_mfma_f32_16x16x32_bf16 v[6:9], v[170:173], v[214:217], v[6:9]
	v_mfma_f32_16x16x32_bf16 v[6:9], v[166:169], v[210:213], v[6:9]
	s_setprio 0
	s_barrier
	s_add_i32 s55, s55, 2
	s_add_u32 s53, s53, 0x100
	s_addc_u32 s54, s54, 0
	s_add_u32 s26, s26, 0x100
	s_addc_u32 s27, s27, 0
	s_cmp_gt_u32 s55, 29

; #define PG8_STAGE(bufoff, gbase, voff) do { _Pragma("unroll") for (int _i = 0; _i < 2; ++_i) \
;         __builtin_amdgcn_global_load_lds((const unsigned*)((const char*)(gbase) + (voff)[_i]), (PG8_LAS unsigned*)(lds + (bufoff) + ldsw + _i * 8192), 16, 0, 0); } while (0)
; #define PG8_LDA(dst, b, h) do { _Pragma("unroll") for (int m = 0; m < 4; ++m) _Pragma("unroll") for (int k = 0; k < 2; ++k) dst[m][k] = *(const PG8_LAS bf16x8*)(lds + PG8_SA(b, h) + aoff + m * 2048 + k * 1024); } while (0)
; #define PG8_LDB(dst, b, h) do { _Pragma("unroll") for (int n = 0; n < 2; ++n) _Pragma("unroll") for (int k = 0; k < 2; ++k) dst[n][k] = *(const PG8_LAS bf16x8*)(lds + PG8_SB(b, h) + boff + n * 2048 + k * 1024); } while (0)
; #define PG8_WAIT_V(n) asm volatile("s_waitcnt vmcnt(" #n ")" ::: "memory")
; #define PG8_WAIT_L(n) asm volatile("s_waitcnt lgkmcnt(" #n ")" ::: "memory")
; #define PG8_BAR __builtin_amdgcn_s_barrier()
; #define PG8_SCHED __builtin_amdgcn_sched_barrier(0)
; template <class Epi, class Sched, bool ALIGN_EPI = false, bool SP2 = false>
; __device__ __forceinline__ void gemm_phase(PG8_LAS unsigned char* lds, const Gemm g, const Sched& S, const Epi& E) {
;     ...
;         const bool has_next = S.next(ui + 1, nxt);
;         const char* nA = has_next ? (const char*)g.A + (size_t)nxt.pm * tstep : cA; const char* nB = has_next ? (const char*)g.Bt + (size_t)nxt.pn * tstep : cB;
;         for (int t = 0; t < nt; t += 2) {
;             const bool last = (t == nt - 2);
;             const char* a1 = cA + (size_t)(t + 1) * kstep;
;             const char* a2 = last ? nA : cA + (size_t)(t + 2) * kstep; const char* b2 = last ? nB : cB + (size_t)(t + 2) * kstep;
;             const char* a3 = a2 + kstep; const char* b3 = b2 + kstep;
;             if (last && has_next) S.a_ready(nxt);
;             if constexpr (Epi::MID) { if (t == nt / 2) E.mid(acc, cur, wr, wc, fr, fq); }
;             if constexpr (SP2) {
;             PG8_LDB(B0, 0, 0); PG8_LDB(B1, 0, 1); PG8_SCHED; PG8_LDA(At, 0, 0); PG8_STAGE(PG8_SA(1, 1), a1 + hstep, voffA);
;             PG8_WAIT_V(8); PG8_WAIT_L(0); PG8_BAR; PG8_MMA(0, 0, At, B0); PG8_MMA(0, 1, At, B1); PG8_BAR; PG8_SCHED;
;             PG8_LDA(At, 0, 1); PG8_STAGE(PG8_SB(0, 0), b2, voffB); PG8_STAGE(PG8_SB(0, 1), b2 + hstep, voffB); PG8_STAGE(PG8_SA(0, 0), a2, voffA);
.LBB0_481:
	s_add_u32 s50, s22, 0x100
	s_addc_u32 s51, s23, 0
	s_mov_b32 s52, -2
	s_add_u32 s22, s20, 0x100
	s_addc_u32 s23, s21, 0
	s_add_i32 s33, 0, 0x10000
	s_cmpk_eq_i32 s52, 0x54
	s_cselect_b32 s27, s5, s23
	s_cselect_b32 s26, s4, s22
	s_cselect_b32 s25, s19, s51
	s_cselect_b32 s24, s18, s50
	s_add_i32 s53, 0, 0x14000
	v_add_u32_e32 v138, s33, v199
	v_add_u32_e32 v162, s53, v199
	ds_read_b128 v[118:121], v138
	ds_read_b128 v[130:133], v138 offset:1024
	ds_read_b128 v[134:137], v138 offset:2048
	ds_read_b128 v[138:141], v138 offset:3072
	ds_read_b128 v[146:149], v162
	ds_read_b128 v[154:157], v162 offset:1024
	ds_read_b128 v[158:161], v162 offset:2048
	ds_read_b128 v[162:165], v162 offset:3072
	v_lshl_add_u64 v[202:203], s[20:21], 0, v[212:213]
	s_add_i32 m0, s37, 0xc000
	ds_read_b128 v[166:169], v201
	ds_read_b128 v[170:173], v201 offset:1024
	ds_read_b128 v[174:177], v201 offset:2048
	ds_read_b128 v[178:181], v201 offset:3072
	ds_read_b128 v[182:185], v201 offset:4096
	ds_read_b128 v[186:189], v201 offset:5120
	ds_read_b128 v[190:193], v201 offset:6144
	ds_read_b128 v[194:197], v201 offset:7168
	global_load_lds_dwordx4 v212, s[20:21]
	v_lshl_add_u64 v[202:203], s[20:21], 0, v[210:211]
	s_add_i32 m0, s37, 0xe000
	s_nop 0
	global_load_lds_dwordx4 v210, s[20:21]
	s_waitcnt vmcnt(8)
	s_waitcnt lgkmcnt(0)
	s_barrier
	s_setprio 1
	s_waitcnt lgkmcnt(0)
	v_mfma_f32_16x16x32_bf16 v[150:153], v[118:121], v[166:169], 0
	v_mfma_f32_16x16x32_bf16 v[150:153], v[130:133], v[170:173], v[150:153]
	v_mfma_f32_16x16x32_bf16 v[142:145], v[138:141], v[170:173], 0
	v_mfma_f32_16x16x32_bf16 v[142:145], v[134:137], v[166:169], v[142:145]
	v_mfma_f32_16x16x32_bf16 v[110:113], v[134:137], v[174:177], 0
	v_mfma_f32_16x16x32_bf16 v[110:113], v[138:141], v[178:181], v[110:113]
	v_mfma_f32_16x16x32_bf16 v[114:117], v[130:133], v[178:181], 0
	v_mfma_f32_16x16x32_bf16 v[114:117], v[118:121], v[174:177], v[114:117]
	v_mfma_f32_16x16x32_bf16 v[98:101], v[118:121], v[182:185], 0
	v_mfma_f32_16x16x32_bf16 v[98:101], v[130:133], v[186:189], v[98:101]
	v_mfma_f32_16x16x32_bf16 v[94:97], v[138:141], v[186:189], 0
	v_mfma_f32_16x16x32_bf16 v[94:97], v[134:137], v[182:185], v[94:97]
	v_mfma_f32_16x16x32_bf16 v[78:81], v[134:137], v[190:193], 0
	v_mfma_f32_16x16x32_bf16 v[78:81], v[138:141], v[194:197], v[78:81]
	v_mfma_f32_16x16x32_bf16 v[82:85], v[130:133], v[194:197], 0
	v_mfma_f32_16x16x32_bf16 v[82:85], v[118:121], v[190:193], v[82:85]
	s_setprio 0
	s_setprio 1
	v_mfma_f32_16x16x32_bf16 v[126:129], v[146:149], v[166:169], 0
	v_mfma_f32_16x16x32_bf16 v[126:129], v[154:157], v[170:173], v[126:129]
	v_mfma_f32_16x16x32_bf16 v[122:125], v[162:165], v[170:173], 0
	v_mfma_f32_16x16x32_bf16 v[122:125], v[158:161], v[166:169], v[122:125]
	v_mfma_f32_16x16x32_bf16 v[102:105], v[158:161], v[174:177], 0
	v_mfma_f32_16x16x32_bf16 v[102:105], v[162:165], v[178:181], v[102:105]
	v_mfma_f32_16x16x32_bf16 v[106:109], v[154:157], v[178:181], 0
	v_mfma_f32_16x16x32_bf16 v[106:109], v[146:149], v[174:177], v[106:109]
	v_mfma_f32_16x16x32_bf16 v[90:93], v[146:149], v[182:185], 0
	v_mfma_f32_16x16x32_bf16 v[90:93], v[154:157], v[186:189], v[90:93]
	v_mfma_f32_16x16x32_bf16 v[86:89], v[162:165], v[186:189], 0
	v_mfma_f32_16x16x32_bf16 v[86:89], v[158:161], v[182:185], v[86:89]
	v_mfma_f32_16x16x32_bf16 v[70:73], v[158:161], v[190:193], 0
	v_mfma_f32_16x16x32_bf16 v[70:73], v[162:165], v[194:197], v[70:73]
	v_mfma_f32_16x16x32_bf16 v[74:77], v[154:157], v[194:197], 0
	v_mfma_f32_16x16x32_bf16 v[74:77], v[146:149], v[190:193], v[74:77]
	s_setprio 0
	s_barrier
	s_add_i32 s20, s33, s36
	v_lshl_add_u64 v[202:203], s[24:25], 0, v[0:1]
	s_mov_b32 m0, s20
	ds_read_b128 v[166:169], v201 offset:16384
	ds_read_b128 v[170:173], v201 offset:17408
	ds_read_b128 v[174:177], v201 offset:18432
	ds_read_b128 v[178:181], v201 offset:19456
	ds_read_b128 v[182:185], v201 offset:20480
	ds_read_b128 v[186:189], v201 offset:21504
	ds_read_b128 v[190:193], v201 offset:22528
	ds_read_b128 v[194:197], v201 offset:23552
	global_load_lds_dwordx4 v0, s[24:25]
	s_add_i32 m0, s20, 0x2000
	s_add_u32 s20, s24, 0x160000
	v_lshl_add_u64 v[214:215], s[24:25], 0, v[208:209]
	s_addc_u32 s21, s25, 0
	s_add_i32 s33, s53, s36
	global_load_lds_dwordx4 v208, s[24:25]
	v_lshl_add_u64 v[216:217], s[20:21], 0, v[0:1]
	s_mov_b32 m0, s33
	v_lshl_add_u64 v[218:219], s[26:27], 0, v[206:207]
	global_load_lds_dwordx4 v0, s[20:21]
	v_lshl_add_u64 v[216:217], s[20:21], 0, v[208:209]
	s_add_i32 m0, s33, 0x2000
	s_nop 0
	global_load_lds_dwordx4 v208, s[20:21]
	v_lshl_add_u64 v[216:217], s[26:27], 0, v[14:15]
	s_mov_b32 m0, s37
	s_nop 0
	global_load_lds_dwordx4 v14, s[26:27]
	s_mov_b32 m0, s38
	s_nop 0
	global_load_lds_dwordx4 v206, s[26:27]
	s_waitcnt vmcnt(8)
	s_waitcnt lgkmcnt(0)
	s_barrier
; #define PG8_STAGE(bufoff, gbase, voff) do { _Pragma("unroll") for (int _i = 0; _i < 2; ++_i) \
;         __builtin_amdgcn_global_load_lds((const unsigned*)((const char*)(gbase) + (voff)[_i]), (PG8_LAS unsigned*)(lds + (bufoff) + ldsw + _i * 8192), 16, 0, 0); } while (0)
; #define PG8_LDA(dst, b, h) do { _Pragma("unroll") for (int m = 0; m < 4; ++m) _Pragma("unroll") for (int k = 0; k < 2; ++k) dst[m][k] = *(const PG8_LAS bf16x8*)(lds + PG8_SA(b, h) + aoff + m * 2048 + k * 1024); } while (0)
; #define PG8_LDB(dst, b, h) do { _Pragma("unroll") for (int n = 0; n < 2; ++n) _Pragma("unroll") for (int k = 0; k < 2; ++k) dst[n][k] = *(const PG8_LAS bf16x8*)(lds + PG8_SB(b, h) + boff + n * 2048 + k * 1024); } while (0)
; #define PG8_MMA(ai, bj, At, Bt) do { __builtin_amdgcn_s_setprio(1); _Pragma("unroll") for (int m = 0; m < 4; ++m) _Pragma("unroll") for (int n = 0; n < 2; ++n) _Pragma("unroll") for (int k = 0; k < 2; ++k) \
;         acc[ai][bj][m][n] = __builtin_amdgcn_mfma_f32_16x16x32_bf16(Bt[n][k], At[m][k], acc[ai][bj][m][n], 0, 0, 0); __builtin_amdgcn_s_setprio(0); } while (0)
; #define PG8_WAIT_V(n) asm volatile("s_waitcnt vmcnt(" #n ")" ::: "memory")
; #define PG8_WAIT_L(n) asm volatile("s_waitcnt lgkmcnt(" #n ")" ::: "memory")
; #define PG8_BAR __builtin_amdgcn_s_barrier()
; #define PG8_SCHED __builtin_amdgcn_sched_barrier(0)
; template <class Epi, class Sched, bool ALIGN_EPI = false, bool SP2 = false>
; __device__ __forceinline__ void gemm_phase(PG8_LAS unsigned char* lds, const Gemm g, const Sched& S, const Epi& E) {
;     ...
;             PG8_WAIT_V(8); PG8_WAIT_L(0); PG8_BAR; PG8_MMA(1, 0, At, B0); PG8_MMA(1, 1, At, B1); PG8_BAR; PG8_SCHED;
;             PG8_LDB(B0, 1, 0); PG8_LDB(B1, 1, 1); PG8_SCHED; PG8_LDA(At, 1, 0); PG8_STAGE(PG8_SA(0, 1), a2 + hstep, voffA);
;             PG8_WAIT_V(8); PG8_WAIT_L(0); PG8_BAR; PG8_MMA(0, 0, At, B0); PG8_MMA(0, 1, At, B1); PG8_BAR; PG8_SCHED;
	s_setprio 1
	s_waitcnt lgkmcnt(0)
	v_mfma_f32_16x16x32_bf16 v[66:69], v[118:121], v[166:169], 0
	v_mfma_f32_16x16x32_bf16 v[66:69], v[130:133], v[170:173], v[66:69]
	v_mfma_f32_16x16x32_bf16 v[62:65], v[138:141], v[170:173], 0
	v_mfma_f32_16x16x32_bf16 v[62:65], v[134:137], v[166:169], v[62:65]
	v_mfma_f32_16x16x32_bf16 v[46:49], v[134:137], v[174:177], 0
	v_mfma_f32_16x16x32_bf16 v[46:49], v[138:141], v[178:181], v[46:49]
	v_mfma_f32_16x16x32_bf16 v[50:53], v[130:133], v[178:181], 0
	v_mfma_f32_16x16x32_bf16 v[50:53], v[118:121], v[174:177], v[50:53]
	v_mfma_f32_16x16x32_bf16 v[34:37], v[118:121], v[182:185], 0
	v_mfma_f32_16x16x32_bf16 v[34:37], v[130:133], v[186:189], v[34:37]
	v_mfma_f32_16x16x32_bf16 v[30:33], v[138:141], v[186:189], 0
	v_mfma_f32_16x16x32_bf16 v[30:33], v[134:137], v[182:185], v[30:33]
	v_mfma_f32_16x16x32_bf16 v[10:13], v[134:137], v[190:193], 0
	v_mfma_f32_16x16x32_bf16 v[10:13], v[138:141], v[194:197], v[10:13]
	v_mfma_f32_16x16x32_bf16 v[18:21], v[130:133], v[194:197], 0
	v_mfma_f32_16x16x32_bf16 v[18:21], v[118:121], v[190:193], v[18:21]
	s_setprio 0
	s_setprio 1
	v_mfma_f32_16x16x32_bf16 v[58:61], v[146:149], v[166:169], 0
	v_mfma_f32_16x16x32_bf16 v[58:61], v[154:157], v[170:173], v[58:61]
	v_mfma_f32_16x16x32_bf16 v[54:57], v[162:165], v[170:173], 0
	v_mfma_f32_16x16x32_bf16 v[54:57], v[158:161], v[166:169], v[54:57]
	v_mfma_f32_16x16x32_bf16 v[38:41], v[158:161], v[174:177], 0
	v_mfma_f32_16x16x32_bf16 v[38:41], v[162:165], v[178:181], v[38:41]
	v_mfma_f32_16x16x32_bf16 v[42:45], v[154:157], v[178:181], 0
	v_mfma_f32_16x16x32_bf16 v[42:45], v[146:149], v[174:177], v[42:45]
	v_mfma_f32_16x16x32_bf16 v[26:29], v[146:149], v[182:185], 0
	v_mfma_f32_16x16x32_bf16 v[26:29], v[154:157], v[186:189], v[26:29]
	v_mfma_f32_16x16x32_bf16 v[22:25], v[162:165], v[186:189], 0
	v_mfma_f32_16x16x32_bf16 v[22:25], v[158:161], v[182:185], v[22:25]
	v_mfma_f32_16x16x32_bf16 v[2:5], v[158:161], v[190:193], 0
	v_mfma_f32_16x16x32_bf16 v[2:5], v[162:165], v[194:197], v[2:5]
	v_mfma_f32_16x16x32_bf16 v[6:9], v[154:157], v[194:197], 0
	v_mfma_f32_16x16x32_bf16 v[6:9], v[146:149], v[190:193], v[6:9]
	s_setprio 0
	s_barrier
	s_add_i32 s33, 0, 0x18000
	s_add_i32 s53, 0, 0x1c000
	v_add_u32_e32 v138, s33, v199
	v_add_u32_e32 v162, s53, v199
	ds_read_b128 v[118:121], v138
	ds_read_b128 v[130:133], v138 offset:1024
	ds_read_b128 v[134:137], v138 offset:2048
	ds_read_b128 v[138:141], v138 offset:3072
	ds_read_b128 v[146:149], v162
	ds_read_b128 v[154:157], v162 offset:1024
	ds_read_b128 v[158:161], v162 offset:2048
	ds_read_b128 v[162:165], v162 offset:3072
	s_add_u32 s20, s26, 0x160000
	s_addc_u32 s21, s27, 0
	s_mov_b32 m0, s39
	v_lshl_add_u64 v[220:221], s[20:21], 0, v[14:15]
	ds_read_b128 v[166:169], v201 offset:32768
	ds_read_b128 v[170:173], v201 offset:33792
	ds_read_b128 v[174:177], v201 offset:34816
	ds_read_b128 v[178:181], v201 offset:35840
	ds_read_b128 v[182:185], v201 offset:36864
	ds_read_b128 v[186:189], v201 offset:37888
	ds_read_b128 v[190:193], v201 offset:38912
	ds_read_b128 v[194:197], v201 offset:39936
	global_load_lds_dwordx4 v14, s[20:21]
	v_lshl_add_u64 v[220:221], s[20:21], 0, v[206:207]
	s_mov_b32 m0, s40
	s_nop 0
	global_load_lds_dwordx4 v206, s[20:21]
	s_waitcnt vmcnt(8)
	s_waitcnt lgkmcnt(0)
	s_barrier
	s_setprio 1
	s_waitcnt lgkmcnt(0)
	v_mfma_f32_16x16x32_bf16 v[150:153], v[118:121], v[166:169], v[150:153]
	v_mfma_f32_16x16x32_bf16 v[150:153], v[130:133], v[170:173], v[150:153]
	v_mfma_f32_16x16x32_bf16 v[142:145], v[138:141], v[170:173], v[142:145]
	v_mfma_f32_16x16x32_bf16 v[142:145], v[134:137], v[166:169], v[142:145]
	v_mfma_f32_16x16x32_bf16 v[110:113], v[134:137], v[174:177], v[110:113]
	v_mfma_f32_16x16x32_bf16 v[110:113], v[138:141], v[178:181], v[110:113]
	v_mfma_f32_16x16x32_bf16 v[114:117], v[130:133], v[178:181], v[114:117]
	v_mfma_f32_16x16x32_bf16 v[114:117], v[118:121], v[174:177], v[114:117]
	v_mfma_f32_16x16x32_bf16 v[98:101], v[118:121], v[182:185], v[98:101]
	v_mfma_f32_16x16x32_bf16 v[98:101], v[130:133], v[186:189], v[98:101]
	v_mfma_f32_16x16x32_bf16 v[94:97], v[138:141], v[186:189], v[94:97]
	v_mfma_f32_16x16x32_bf16 v[94:97], v[134:137], v[182:185], v[94:97]
	v_mfma_f32_16x16x32_bf16 v[78:81], v[134:137], v[190:193], v[78:81]
	v_mfma_f32_16x16x32_bf16 v[78:81], v[138:141], v[194:197], v[78:81]
	v_mfma_f32_16x16x32_bf16 v[82:85], v[130:133], v[194:197], v[82:85]
	v_mfma_f32_16x16x32_bf16 v[82:85], v[118:121], v[190:193], v[82:85]
	s_setprio 0
	s_setprio 1
	v_mfma_f32_16x16x32_bf16 v[126:129], v[146:149], v[166:169], v[126:129]
	v_mfma_f32_16x16x32_bf16 v[126:129], v[154:157], v[170:173], v[126:129]
	v_mfma_f32_16x16x32_bf16 v[122:125], v[162:165], v[170:173], v[122:125]
	v_mfma_f32_16x16x32_bf16 v[122:125], v[158:161], v[166:169], v[122:125]
	v_mfma_f32_16x16x32_bf16 v[102:105], v[158:161], v[174:177], v[102:105]
	v_mfma_f32_16x16x32_bf16 v[102:105], v[162:165], v[178:181], v[102:105]
	v_mfma_f32_16x16x32_bf16 v[106:109], v[154:157], v[178:181], v[106:109]
	v_mfma_f32_16x16x32_bf16 v[106:109], v[146:149], v[174:177], v[106:109]
	v_mfma_f32_16x16x32_bf16 v[90:93], v[146:149], v[182:185], v[90:93]
	v_mfma_f32_16x16x32_bf16 v[90:93], v[154:157], v[186:189], v[90:93]
	v_mfma_f32_16x16x32_bf16 v[86:89], v[162:165], v[186:189], v[86:89]
	v_mfma_f32_16x16x32_bf16 v[86:89], v[158:161], v[182:185], v[86:89]
	v_mfma_f32_16x16x32_bf16 v[70:73], v[158:161], v[190:193], v[70:73]
	v_mfma_f32_16x16x32_bf16 v[70:73], v[162:165], v[194:197], v[70:73]
	v_mfma_f32_16x16x32_bf16 v[74:77], v[154:157], v[194:197], v[74:77]
	v_mfma_f32_16x16x32_bf16 v[74:77], v[146:149], v[190:193], v[74:77]
	s_setprio 0
	s_barrier
; #define PG8_STAGE(bufoff, gbase, voff) do { _Pragma("unroll") for (int _i = 0; _i < 2; ++_i) \
;         __builtin_amdgcn_global_load_lds((const unsigned*)((const char*)(gbase) + (voff)[_i]), (PG8_LAS unsigned*)(lds + (bufoff) + ldsw + _i * 8192), 16, 0, 0); } while (0)
; #define PG8_LDA(dst, b, h) do { _Pragma("unroll") for (int m = 0; m < 4; ++m) _Pragma("unroll") for (int k = 0; k < 2; ++k) dst[m][k] = *(const PG8_LAS bf16x8*)(lds + PG8_SA(b, h) + aoff + m * 2048 + k * 1024); } while (0)
; #define PG8_MMA(ai, bj, At, Bt) do { __builtin_amdgcn_s_setprio(1); _Pragma("unroll") for (int m = 0; m < 4; ++m) _Pragma("unroll") for (int n = 0; n < 2; ++n) _Pragma("unroll") for (int k = 0; k < 2; ++k) \
;         acc[ai][bj][m][n] = __builtin_amdgcn_mfma_f32_16x16x32_bf16(Bt[n][k], At[m][k], acc[ai][bj][m][n], 0, 0, 0); __builtin_amdgcn_s_setprio(0); } while (0)
; #define PG8_WAIT_V(n) asm volatile("s_waitcnt vmcnt(" #n ")" ::: "memory")
; #define PG8_WAIT_L(n) asm volatile("s_waitcnt lgkmcnt(" #n ")" ::: "memory")
; #define PG8_BAR __builtin_amdgcn_s_barrier()
; #define PG8_SCHED __builtin_amdgcn_sched_barrier(0)
; template <class Epi, class Sched, bool ALIGN_EPI = false, bool SP2 = false>
; __device__ __forceinline__ void gemm_phase(PG8_LAS unsigned char* lds, const Gemm g, const Sched& S, const Epi& E) {
;     ...
;             PG8_LDA(At, 1, 1); PG8_STAGE(PG8_SB(1, 0), b3, voffB); PG8_STAGE(PG8_SB(1, 1), b3 + hstep, voffB); PG8_STAGE(PG8_SA(1, 0), a3, voffA);
;             PG8_WAIT_V(8); PG8_WAIT_L(0); PG8_BAR; PG8_MMA(1, 0, At, B0); PG8_MMA(1, 1, At, B1); PG8_BAR; PG8_SCHED;
	s_add_i32 s20, s33, s36
	v_lshl_add_u64 v[202:203], v[202:203], 0, s[92:93]
	s_mov_b32 m0, s20
	ds_read_b128 v[166:169], v201 offset:49152
	ds_read_b128 v[170:173], v201 offset:50176
	ds_read_b128 v[174:177], v201 offset:51200
	ds_read_b128 v[178:181], v201 offset:52224
	ds_read_b128 v[182:185], v201 offset:53248
	ds_read_b128 v[186:189], v201 offset:54272
	ds_read_b128 v[190:193], v201 offset:55296
	ds_read_b128 v[194:197], v201 offset:56320
	global_load_lds_dwordx4 v[202:203], off
	s_add_i32 m0, s20, 0x2000
	s_add_u32 s20, s24, 0x160080
	v_lshl_add_u64 v[202:203], v[214:215], 0, s[92:93]
	s_addc_u32 s21, s25, 0
	s_add_i32 s24, s53, s36
	global_load_lds_dwordx4 v[202:203], off
	v_lshl_add_u64 v[202:203], s[20:21], 0, v[0:1]
	s_mov_b32 m0, s24
	s_nop 0
	global_load_lds_dwordx4 v0, s[20:21]
	v_lshl_add_u64 v[202:203], s[20:21], 0, v[208:209]
	s_add_i32 m0, s24, 0x2000
	s_nop 0
	global_load_lds_dwordx4 v208, s[20:21]
	v_lshl_add_u64 v[202:203], v[216:217], 0, s[92:93]
	s_mov_b32 m0, s42
	s_nop 0
	global_load_lds_dwordx4 v[202:203], off
	v_lshl_add_u64 v[202:203], v[218:219], 0, s[92:93]
	s_mov_b32 m0, s43
	s_nop 0
	global_load_lds_dwordx4 v[202:203], off
	s_waitcnt vmcnt(8)
	s_waitcnt lgkmcnt(0)
	s_barrier
	s_setprio 1
	s_waitcnt lgkmcnt(0)
	v_mfma_f32_16x16x32_bf16 v[66:69], v[118:121], v[166:169], v[66:69]
	v_mfma_f32_16x16x32_bf16 v[66:69], v[130:133], v[170:173], v[66:69]
	v_mfma_f32_16x16x32_bf16 v[62:65], v[138:141], v[170:173], v[62:65]
	v_mfma_f32_16x16x32_bf16 v[62:65], v[134:137], v[166:169], v[62:65]
	v_mfma_f32_16x16x32_bf16 v[46:49], v[134:137], v[174:177], v[46:49]
	v_mfma_f32_16x16x32_bf16 v[46:49], v[138:141], v[178:181], v[46:49]
	v_mfma_f32_16x16x32_bf16 v[50:53], v[130:133], v[178:181], v[50:53]
	v_mfma_f32_16x16x32_bf16 v[50:53], v[118:121], v[174:177], v[50:53]
	v_mfma_f32_16x16x32_bf16 v[34:37], v[118:121], v[182:185], v[34:37]
	v_mfma_f32_16x16x32_bf16 v[34:37], v[130:133], v[186:189], v[34:37]
	v_mfma_f32_16x16x32_bf16 v[30:33], v[138:141], v[186:189], v[30:33]
	v_mfma_f32_16x16x32_bf16 v[30:33], v[134:137], v[182:185], v[30:33]
	v_mfma_f32_16x16x32_bf16 v[10:13], v[134:137], v[190:193], v[10:13]
	v_mfma_f32_16x16x32_bf16 v[10:13], v[138:141], v[194:197], v[10:13]
	v_mfma_f32_16x16x32_bf16 v[18:21], v[130:133], v[194:197], v[18:21]
	v_mfma_f32_16x16x32_bf16 v[18:21], v[118:121], v[190:193], v[18:21]
	s_setprio 0
	s_setprio 1
	v_mfma_f32_16x16x32_bf16 v[58:61], v[146:149], v[166:169], v[58:61]
	v_mfma_f32_16x16x32_bf16 v[58:61], v[154:157], v[170:173], v[58:61]
	v_mfma_f32_16x16x32_bf16 v[54:57], v[162:165], v[170:173], v[54:57]
	v_mfma_f32_16x16x32_bf16 v[54:57], v[158:161], v[166:169], v[54:57]
	v_mfma_f32_16x16x32_bf16 v[38:41], v[158:161], v[174:177], v[38:41]
	v_mfma_f32_16x16x32_bf16 v[38:41], v[162:165], v[178:181], v[38:41]
	v_mfma_f32_16x16x32_bf16 v[42:45], v[154:157], v[178:181], v[42:45]
	v_mfma_f32_16x16x32_bf16 v[42:45], v[146:149], v[174:177], v[42:45]
	v_mfma_f32_16x16x32_bf16 v[26:29], v[146:149], v[182:185], v[26:29]
	v_mfma_f32_16x16x32_bf16 v[26:29], v[154:157], v[186:189], v[26:29]
	v_mfma_f32_16x16x32_bf16 v[22:25], v[162:165], v[186:189], v[22:25]
	v_mfma_f32_16x16x32_bf16 v[22:25], v[158:161], v[182:185], v[22:25]
	v_mfma_f32_16x16x32_bf16 v[2:5], v[158:161], v[190:193], v[2:5]
	v_mfma_f32_16x16x32_bf16 v[2:5], v[162:165], v[194:197], v[2:5]
	v_mfma_f32_16x16x32_bf16 v[6:9], v[154:157], v[194:197], v[6:9]
	v_mfma_f32_16x16x32_bf16 v[6:9], v[146:149], v[190:193], v[6:9]
	s_setprio 0
	s_barrier
	s_add_i32 s52, s52, 2
	s_add_u32 s50, s50, 0x100
	s_addc_u32 s51, s51, 0
	s_cmpk_gt_u32 s52, 0x55
	s_mov_b64 s[20:21], s[22:23]

; #define PG8_STAGE(bufoff, gbase, voff) do { _Pragma("unroll") for (int _i = 0; _i < 2; ++_i) \
;         __builtin_amdgcn_global_load_lds((const unsigned*)((const char*)(gbase) + (voff)[_i]), (PG8_LAS unsigned*)(lds + (bufoff) + ldsw + _i * 8192), 16, 0, 0); } while (0)
; #define PG8_LDA(dst, b, h) do { _Pragma("unroll") for (int m = 0; m < 4; ++m) _Pragma("unroll") for (int k = 0; k < 2; ++k) dst[m][k] = *(const PG8_LAS bf16x8*)(lds + PG8_SA(b, h) + aoff + m * 2048 + k * 1024); } while (0)
; #define PG8_LDB(dst, b, h) do { _Pragma("unroll") for (int n = 0; n < 2; ++n) _Pragma("unroll") for (int k = 0; k < 2; ++k) dst[n][k] = *(const PG8_LAS bf16x8*)(lds + PG8_SB(b, h) + boff + n * 2048 + k * 1024); } while (0)
; #define PG8_WAIT_V(n) asm volatile("s_waitcnt vmcnt(" #n ")" ::: "memory")
; #define PG8_WAIT_L(n) asm volatile("s_waitcnt lgkmcnt(" #n ")" ::: "memory")
; #define PG8_BAR __builtin_amdgcn_s_barrier()
; #define PG8_SCHED __builtin_amdgcn_sched_barrier(0)
; template <class Epi, class Sched, bool ALIGN_EPI = false, bool SP2 = false>
; __device__ __forceinline__ void gemm_phase(PG8_LAS unsigned char* lds, const Gemm g, const Sched& S, const Epi& E) {
;     ...
;         const bool has_next = S.next(ui + 1, nxt);
;         const char* nA = has_next ? (const char*)g.A + (size_t)nxt.pm * tstep : cA; const char* nB = has_next ? (const char*)g.Bt + (size_t)nxt.pn * tstep : cB;
;         for (int t = 0; t < nt; t += 2) {
;             const bool last = (t == nt - 2);
;             const char* a1 = cA + (size_t)(t + 1) * kstep;
;             const char* a2 = last ? nA : cA + (size_t)(t + 2) * kstep; const char* b2 = last ? nB : cB + (size_t)(t + 2) * kstep;
;             const char* a3 = a2 + kstep; const char* b3 = b2 + kstep;
;             if (last && has_next) S.a_ready(nxt);
;             if constexpr (Epi::MID) { if (t == nt / 2) E.mid(acc, cur, wr, wc, fr, fq); }
;             if constexpr (SP2) {
;             PG8_LDB(B0, 0, 0); PG8_LDB(B1, 0, 1); PG8_SCHED; PG8_LDA(At, 0, 0); PG8_STAGE(PG8_SA(1, 1), a1 + hstep, voffA);
;             PG8_WAIT_V(8); PG8_WAIT_L(0); PG8_BAR; PG8_MMA(0, 0, At, B0); PG8_MMA(0, 1, At, B1); PG8_BAR; PG8_SCHED;
;             PG8_LDA(At, 0, 1); PG8_STAGE(PG8_SB(0, 0), b2, voffB); PG8_STAGE(PG8_SB(0, 1), b2 + hstep, voffB); PG8_STAGE(PG8_SA(0, 0), a2, voffA);
.LBB0_587:
	s_ashr_i32 s35, s34, 31
	s_lshl_b64 s[36:37], s[34:35], 20
	s_add_u32 s36, s6, s36
	s_addc_u32 s37, s7, s37
	s_and_b64 s[38:39], s[2:3], exec
	s_cselect_b32 s5, s37, s45
	s_cselect_b32 s13, s36, s44
	s_ashr_i32 s31, s30, 31
	s_lshl_b64 s[38:39], s[30:31], 20
	s_add_u32 s38, s59, s38
	s_addc_u32 s39, s60, s39
	s_and_b64 s[46:47], s[2:3], exec
	s_cselect_b32 s31, s39, s41
	s_cselect_b32 s35, s38, s40
	s_add_u32 s43, s40, 0x100
	s_addc_u32 s48, s41, 0
	s_add_u32 s40, s44, 0x80080
	s_addc_u32 s41, s45, 0
	s_mov_b32 s49, -2
	s_add_u32 s33, s40, 0xfff80080
	s_addc_u32 s44, s41, -1
	s_add_i32 s50, 0, 0x10000
	s_cmp_eq_u32 s49, 28
	s_cselect_b32 s47, s5, s44
	s_cselect_b32 s46, s13, s33
	v_add_u32_e32 v0, s50, v153
	s_cselect_b32 s45, s31, s48
	s_cselect_b32 s44, s35, s43
	s_add_i32 s33, 0, 0x14000
	ds_read_b128 v[134:137], v0
	ds_read_b128 v[138:141], v0 offset:1024
	ds_read_b128 v[142:145], v0 offset:2048
	s_waitcnt lgkmcnt(0)
	ds_read_b128 v[168:171], v0 offset:3072
	v_add_u32_e32 v0, s33, v153
	ds_read_b128 v[172:175], v0
	ds_read_b128 v[176:179], v0 offset:1024
	ds_read_b128 v[180:183], v0 offset:2048
	ds_read_b128 v[184:187], v0 offset:3072
	v_lshl_add_u64 v[192:193], s[40:41], 0, v[166:167]
	s_add_i32 m0, s62, 0xc000
	ds_read_b128 v[188:191], v194
	ds_read_b128 v[196:199], v194 offset:1024
	ds_read_b128 v[200:203], v194 offset:2048
	ds_read_b128 v[206:209], v194 offset:3072
	ds_read_b128 v[210:213], v194 offset:4096
	ds_read_b128 v[214:217], v194 offset:5120
	ds_read_b128 v[218:221], v194 offset:6144
	ds_read_b128 v[222:225], v194 offset:7168
	global_load_lds_dwordx4 v166, s[40:41]
	v_lshl_add_u64 v[192:193], s[40:41], 0, v[164:165]
	s_add_i32 m0, s62, 0xe000
	s_nop 0
	global_load_lds_dwordx4 v164, s[40:41]
	s_waitcnt vmcnt(8)
	s_waitcnt lgkmcnt(0)
	s_barrier
	s_setprio 1
	s_waitcnt lgkmcnt(0)
	v_mfma_f32_16x16x32_bf16 v[74:77], v[134:137], v[188:191], 0
	v_mfma_f32_16x16x32_bf16 v[74:77], v[138:141], v[196:199], v[74:77]
	v_mfma_f32_16x16x32_bf16 v[62:65], v[168:171], v[196:199], 0
	v_mfma_f32_16x16x32_bf16 v[62:65], v[142:145], v[188:191], v[62:65]
	v_mfma_f32_16x16x32_bf16 v[54:57], v[142:145], v[200:203], 0
	v_mfma_f32_16x16x32_bf16 v[54:57], v[168:171], v[206:209], v[54:57]
	v_mfma_f32_16x16x32_bf16 v[58:61], v[138:141], v[206:209], 0
	v_mfma_f32_16x16x32_bf16 v[58:61], v[134:137], v[200:203], v[58:61]
	v_mfma_f32_16x16x32_bf16 v[50:53], v[134:137], v[210:213], 0
	v_mfma_f32_16x16x32_bf16 v[50:53], v[138:141], v[214:217], v[50:53]
	v_mfma_f32_16x16x32_bf16 v[46:49], v[168:171], v[214:217], 0
	v_mfma_f32_16x16x32_bf16 v[46:49], v[142:145], v[210:213], v[46:49]
	v_mfma_f32_16x16x32_bf16 v[38:41], v[142:145], v[218:221], 0
	v_mfma_f32_16x16x32_bf16 v[38:41], v[168:171], v[222:225], v[38:41]
	v_mfma_f32_16x16x32_bf16 v[42:45], v[138:141], v[222:225], 0
	v_mfma_f32_16x16x32_bf16 v[42:45], v[134:137], v[218:221], v[42:45]
	s_setprio 0
	s_setprio 1
	v_mfma_f32_16x16x32_bf16 v[130:133], v[172:175], v[188:191], 0
	v_mfma_f32_16x16x32_bf16 v[130:133], v[176:179], v[196:199], v[130:133]
	v_mfma_f32_16x16x32_bf16 v[126:129], v[184:187], v[196:199], 0
	v_mfma_f32_16x16x32_bf16 v[126:129], v[180:183], v[188:191], v[126:129]
	v_mfma_f32_16x16x32_bf16 v[118:121], v[180:183], v[200:203], 0
	v_mfma_f32_16x16x32_bf16 v[118:121], v[184:187], v[206:209], v[118:121]
	v_mfma_f32_16x16x32_bf16 v[122:125], v[176:179], v[206:209], 0
	v_mfma_f32_16x16x32_bf16 v[122:125], v[172:175], v[200:203], v[122:125]
	v_mfma_f32_16x16x32_bf16 v[114:117], v[172:175], v[210:213], 0
	v_mfma_f32_16x16x32_bf16 v[114:117], v[176:179], v[214:217], v[114:117]
	v_mfma_f32_16x16x32_bf16 v[110:113], v[184:187], v[214:217], 0
	v_mfma_f32_16x16x32_bf16 v[110:113], v[180:183], v[210:213], v[110:113]
	v_mfma_f32_16x16x32_bf16 v[102:105], v[180:183], v[218:221], 0
	v_mfma_f32_16x16x32_bf16 v[102:105], v[184:187], v[222:225], v[102:105]
	v_mfma_f32_16x16x32_bf16 v[106:109], v[176:179], v[222:225], 0
	v_mfma_f32_16x16x32_bf16 v[106:109], v[172:175], v[218:221], v[106:109]
	s_setprio 0
	s_barrier
	s_add_i32 s50, s50, s61
	v_lshl_add_u64 v[192:193], s[44:45], 0, v[146:147]
	s_mov_b32 m0, s50
	ds_read_b128 v[188:191], v194 offset:16384
	ds_read_b128 v[196:199], v194 offset:17408
	ds_read_b128 v[200:203], v194 offset:18432
	ds_read_b128 v[206:209], v194 offset:19456
	ds_read_b128 v[210:213], v194 offset:20480
	ds_read_b128 v[214:217], v194 offset:21504
	ds_read_b128 v[218:221], v194 offset:22528
	ds_read_b128 v[222:225], v194 offset:23552
	global_load_lds_dwordx4 v146, s[44:45]
	s_add_i32 m0, s50, 0x2000
	s_add_u32 s50, s44, 0x80000
	v_lshl_add_u64 v[226:227], s[44:45], 0, v[150:151]
	s_addc_u32 s51, s45, 0
	s_add_i32 s33, s33, s61
	global_load_lds_dwordx4 v150, s[44:45]
	v_lshl_add_u64 v[228:229], s[50:51], 0, v[146:147]
	s_mov_b32 m0, s33
	v_lshl_add_u64 v[230:231], s[46:47], 0, v[148:149]
	global_load_lds_dwordx4 v146, s[50:51]
	v_lshl_add_u64 v[228:229], s[50:51], 0, v[150:151]
	s_add_i32 m0, s33, 0x2000
	s_nop 0
	global_load_lds_dwordx4 v150, s[50:51]
	v_lshl_add_u64 v[228:229], s[46:47], 0, v[14:15]
	s_mov_b32 m0, s62
	s_nop 0
	global_load_lds_dwordx4 v14, s[46:47]
	s_mov_b32 m0, s63
	s_nop 0
	global_load_lds_dwordx4 v148, s[46:47]
	s_waitcnt vmcnt(8)
	s_waitcnt lgkmcnt(0)
	s_barrier
; #define PG8_STAGE(bufoff, gbase, voff) do { _Pragma("unroll") for (int _i = 0; _i < 2; ++_i) \
;         __builtin_amdgcn_global_load_lds((const unsigned*)((const char*)(gbase) + (voff)[_i]), (PG8_LAS unsigned*)(lds + (bufoff) + ldsw + _i * 8192), 16, 0, 0); } while (0)
; #define PG8_LDA(dst, b, h) do { _Pragma("unroll") for (int m = 0; m < 4; ++m) _Pragma("unroll") for (int k = 0; k < 2; ++k) dst[m][k] = *(const PG8_LAS bf16x8*)(lds + PG8_SA(b, h) + aoff + m * 2048 + k * 1024); } while (0)
; #define PG8_LDB(dst, b, h) do { _Pragma("unroll") for (int n = 0; n < 2; ++n) _Pragma("unroll") for (int k = 0; k < 2; ++k) dst[n][k] = *(const PG8_LAS bf16x8*)(lds + PG8_SB(b, h) + boff + n * 2048 + k * 1024); } while (0)
; #define PG8_MMA(ai, bj, At, Bt) do { __builtin_amdgcn_s_setprio(1); _Pragma("unroll") for (int m = 0; m < 4; ++m) _Pragma("unroll") for (int n = 0; n < 2; ++n) _Pragma("unroll") for (int k = 0; k < 2; ++k) \
;         acc[ai][bj][m][n] = __builtin_amdgcn_mfma_f32_16x16x32_bf16(Bt[n][k], At[m][k], acc[ai][bj][m][n], 0, 0, 0); __builtin_amdgcn_s_setprio(0); } while (0)
; #define PG8_WAIT_V(n) asm volatile("s_waitcnt vmcnt(" #n ")" ::: "memory")
; #define PG8_WAIT_L(n) asm volatile("s_waitcnt lgkmcnt(" #n ")" ::: "memory")
; #define PG8_BAR __builtin_amdgcn_s_barrier()
; #define PG8_SCHED __builtin_amdgcn_sched_barrier(0)
; template <class Epi, class Sched, bool ALIGN_EPI = false, bool SP2 = false>
; __device__ __forceinline__ void gemm_phase(PG8_LAS unsigned char* lds, const Gemm g, const Sched& S, const Epi& E) {
;     ...
;             PG8_WAIT_V(8); PG8_WAIT_L(0); PG8_BAR; PG8_MMA(1, 0, At, B0); PG8_MMA(1, 1, At, B1); PG8_BAR; PG8_SCHED;
;             PG8_LDB(B0, 1, 0); PG8_LDB(B1, 1, 1); PG8_SCHED; PG8_LDA(At, 1, 0); PG8_STAGE(PG8_SA(0, 1), a2 + hstep, voffA);
;             PG8_WAIT_V(8); PG8_WAIT_L(0); PG8_BAR; PG8_MMA(0, 0, At, B0); PG8_MMA(0, 1, At, B1); PG8_BAR; PG8_SCHED;
	s_setprio 1
	s_waitcnt lgkmcnt(0)
	v_mfma_f32_16x16x32_bf16 v[34:37], v[134:137], v[188:191], 0
	v_mfma_f32_16x16x32_bf16 v[34:37], v[138:141], v[196:199], v[34:37]
	v_mfma_f32_16x16x32_bf16 v[30:33], v[168:171], v[196:199], 0
	v_mfma_f32_16x16x32_bf16 v[30:33], v[142:145], v[188:191], v[30:33]
	v_mfma_f32_16x16x32_bf16 v[22:25], v[142:145], v[200:203], 0
	v_mfma_f32_16x16x32_bf16 v[22:25], v[168:171], v[206:209], v[22:25]
	v_mfma_f32_16x16x32_bf16 v[26:29], v[138:141], v[206:209], 0
	v_mfma_f32_16x16x32_bf16 v[26:29], v[134:137], v[200:203], v[26:29]
	v_mfma_f32_16x16x32_bf16 v[18:21], v[134:137], v[210:213], 0
	v_mfma_f32_16x16x32_bf16 v[18:21], v[138:141], v[214:217], v[18:21]
	v_mfma_f32_16x16x32_bf16 v[10:13], v[168:171], v[214:217], 0
	v_mfma_f32_16x16x32_bf16 v[10:13], v[142:145], v[210:213], v[10:13]
	v_mfma_f32_16x16x32_bf16 v[2:5], v[142:145], v[218:221], 0
	v_mfma_f32_16x16x32_bf16 v[2:5], v[168:171], v[222:225], v[2:5]
	v_mfma_f32_16x16x32_bf16 v[6:9], v[138:141], v[222:225], 0
	v_mfma_f32_16x16x32_bf16 v[6:9], v[134:137], v[218:221], v[6:9]
	s_setprio 0
	s_setprio 1
	v_mfma_f32_16x16x32_bf16 v[98:101], v[172:175], v[188:191], 0
	v_mfma_f32_16x16x32_bf16 v[98:101], v[176:179], v[196:199], v[98:101]
	v_mfma_f32_16x16x32_bf16 v[94:97], v[184:187], v[196:199], 0
	v_mfma_f32_16x16x32_bf16 v[94:97], v[180:183], v[188:191], v[94:97]
	v_mfma_f32_16x16x32_bf16 v[86:89], v[180:183], v[200:203], 0
	v_mfma_f32_16x16x32_bf16 v[86:89], v[184:187], v[206:209], v[86:89]
	v_mfma_f32_16x16x32_bf16 v[90:93], v[176:179], v[206:209], 0
	v_mfma_f32_16x16x32_bf16 v[90:93], v[172:175], v[200:203], v[90:93]
	v_mfma_f32_16x16x32_bf16 v[82:85], v[172:175], v[210:213], 0
	v_mfma_f32_16x16x32_bf16 v[82:85], v[176:179], v[214:217], v[82:85]
	v_mfma_f32_16x16x32_bf16 v[78:81], v[184:187], v[214:217], 0
	v_mfma_f32_16x16x32_bf16 v[78:81], v[180:183], v[210:213], v[78:81]
	v_mfma_f32_16x16x32_bf16 v[66:69], v[180:183], v[218:221], 0
	v_mfma_f32_16x16x32_bf16 v[66:69], v[184:187], v[222:225], v[66:69]
	v_mfma_f32_16x16x32_bf16 v[70:73], v[176:179], v[222:225], 0
	v_mfma_f32_16x16x32_bf16 v[70:73], v[172:175], v[218:221], v[70:73]
	s_setprio 0
	s_barrier
	s_add_i32 s33, 0, 0x18000
	v_add_u32_e32 v0, s33, v153
	s_add_i32 s50, 0, 0x1c000
	ds_read_b128 v[134:137], v0
	ds_read_b128 v[138:141], v0 offset:1024
	ds_read_b128 v[142:145], v0 offset:2048
	ds_read_b128 v[168:171], v0 offset:3072
	v_add_u32_e32 v0, s50, v153
	ds_read_b128 v[172:175], v0
	ds_read_b128 v[176:179], v0 offset:1024
	ds_read_b128 v[180:183], v0 offset:2048
	ds_read_b128 v[184:187], v0 offset:3072
	s_add_u32 s46, s46, 0x80000
	s_addc_u32 s47, s47, 0
	s_mov_b32 m0, s64
	v_lshl_add_u64 v[232:233], s[46:47], 0, v[14:15]
	ds_read_b128 v[188:191], v194 offset:32768
	ds_read_b128 v[196:199], v194 offset:33792
	ds_read_b128 v[200:203], v194 offset:34816
	ds_read_b128 v[206:209], v194 offset:35840
	ds_read_b128 v[210:213], v194 offset:36864
	ds_read_b128 v[214:217], v194 offset:37888
	ds_read_b128 v[218:221], v194 offset:38912
	ds_read_b128 v[222:225], v194 offset:39936
	global_load_lds_dwordx4 v14, s[46:47]
	v_lshl_add_u64 v[232:233], s[46:47], 0, v[148:149]
	s_mov_b32 m0, s65
	s_nop 0
	global_load_lds_dwordx4 v148, s[46:47]
	s_waitcnt vmcnt(8)
	s_waitcnt lgkmcnt(0)
	s_barrier
	s_setprio 1
	s_waitcnt lgkmcnt(0)
	v_mfma_f32_16x16x32_bf16 v[74:77], v[134:137], v[188:191], v[74:77]
	v_mfma_f32_16x16x32_bf16 v[74:77], v[138:141], v[196:199], v[74:77]
	v_mfma_f32_16x16x32_bf16 v[62:65], v[168:171], v[196:199], v[62:65]
	v_mfma_f32_16x16x32_bf16 v[62:65], v[142:145], v[188:191], v[62:65]
	v_mfma_f32_16x16x32_bf16 v[54:57], v[142:145], v[200:203], v[54:57]
	v_mfma_f32_16x16x32_bf16 v[54:57], v[168:171], v[206:209], v[54:57]
	v_mfma_f32_16x16x32_bf16 v[58:61], v[138:141], v[206:209], v[58:61]
	v_mfma_f32_16x16x32_bf16 v[58:61], v[134:137], v[200:203], v[58:61]
	v_mfma_f32_16x16x32_bf16 v[50:53], v[134:137], v[210:213], v[50:53]
	v_mfma_f32_16x16x32_bf16 v[50:53], v[138:141], v[214:217], v[50:53]
	v_mfma_f32_16x16x32_bf16 v[46:49], v[168:171], v[214:217], v[46:49]
	v_mfma_f32_16x16x32_bf16 v[46:49], v[142:145], v[210:213], v[46:49]
	v_mfma_f32_16x16x32_bf16 v[38:41], v[142:145], v[218:221], v[38:41]
	v_mfma_f32_16x16x32_bf16 v[38:41], v[168:171], v[222:225], v[38:41]
	v_mfma_f32_16x16x32_bf16 v[42:45], v[138:141], v[222:225], v[42:45]
	v_mfma_f32_16x16x32_bf16 v[42:45], v[134:137], v[218:221], v[42:45]
	s_setprio 0
	s_setprio 1
	v_mfma_f32_16x16x32_bf16 v[130:133], v[172:175], v[188:191], v[130:133]
	v_mfma_f32_16x16x32_bf16 v[130:133], v[176:179], v[196:199], v[130:133]
	v_mfma_f32_16x16x32_bf16 v[126:129], v[184:187], v[196:199], v[126:129]
	v_mfma_f32_16x16x32_bf16 v[126:129], v[180:183], v[188:191], v[126:129]
	v_mfma_f32_16x16x32_bf16 v[118:121], v[180:183], v[200:203], v[118:121]
	v_mfma_f32_16x16x32_bf16 v[118:121], v[184:187], v[206:209], v[118:121]
	v_mfma_f32_16x16x32_bf16 v[122:125], v[176:179], v[206:209], v[122:125]
	v_mfma_f32_16x16x32_bf16 v[122:125], v[172:175], v[200:203], v[122:125]
	v_mfma_f32_16x16x32_bf16 v[114:117], v[172:175], v[210:213], v[114:117]
	v_mfma_f32_16x16x32_bf16 v[114:117], v[176:179], v[214:217], v[114:117]
	v_mfma_f32_16x16x32_bf16 v[110:113], v[184:187], v[214:217], v[110:113]
	v_mfma_f32_16x16x32_bf16 v[110:113], v[180:183], v[210:213], v[110:113]
	v_mfma_f32_16x16x32_bf16 v[102:105], v[180:183], v[218:221], v[102:105]
	v_mfma_f32_16x16x32_bf16 v[102:105], v[184:187], v[222:225], v[102:105]
	v_mfma_f32_16x16x32_bf16 v[106:109], v[176:179], v[222:225], v[106:109]
	v_mfma_f32_16x16x32_bf16 v[106:109], v[172:175], v[218:221], v[106:109]
	s_setprio 0
	s_barrier
; #define PG8_STAGE(bufoff, gbase, voff) do { _Pragma("unroll") for (int _i = 0; _i < 2; ++_i) \
;         __builtin_amdgcn_global_load_lds((const unsigned*)((const char*)(gbase) + (voff)[_i]), (PG8_LAS unsigned*)(lds + (bufoff) + ldsw + _i * 8192), 16, 0, 0); } while (0)
; #define PG8_LDA(dst, b, h) do { _Pragma("unroll") for (int m = 0; m < 4; ++m) _Pragma("unroll") for (int k = 0; k < 2; ++k) dst[m][k] = *(const PG8_LAS bf16x8*)(lds + PG8_SA(b, h) + aoff + m * 2048 + k * 1024); } while (0)
; #define PG8_MMA(ai, bj, At, Bt) do { __builtin_amdgcn_s_setprio(1); _Pragma("unroll") for (int m = 0; m < 4; ++m) _Pragma("unroll") for (int n = 0; n < 2; ++n) _Pragma("unroll") for (int k = 0; k < 2; ++k) \
;         acc[ai][bj][m][n] = __builtin_amdgcn_mfma_f32_16x16x32_bf16(Bt[n][k], At[m][k], acc[ai][bj][m][n], 0, 0, 0); __builtin_amdgcn_s_setprio(0); } while (0)
; #define PG8_WAIT_V(n) asm volatile("s_waitcnt vmcnt(" #n ")" ::: "memory")
; #define PG8_WAIT_L(n) asm volatile("s_waitcnt lgkmcnt(" #n ")" ::: "memory")
; #define PG8_BAR __builtin_amdgcn_s_barrier()
; #define PG8_SCHED __builtin_amdgcn_sched_barrier(0)
; template <class Epi, class Sched, bool ALIGN_EPI = false, bool SP2 = false>
; __device__ __forceinline__ void gemm_phase(PG8_LAS unsigned char* lds, const Gemm g, const Sched& S, const Epi& E) {
;     ...
;             PG8_LDA(At, 1, 1); PG8_STAGE(PG8_SB(1, 0), b3, voffB); PG8_STAGE(PG8_SB(1, 1), b3 + hstep, voffB); PG8_STAGE(PG8_SA(1, 0), a3, voffA);
;             PG8_WAIT_V(8); PG8_WAIT_L(0); PG8_BAR; PG8_MMA(1, 0, At, B0); PG8_MMA(1, 1, At, B1); PG8_BAR; PG8_SCHED;
	s_add_i32 s33, s33, s61
	v_lshl_add_u64 v[192:193], v[192:193], 0, s[92:93]
	s_mov_b32 m0, s33
	ds_read_b128 v[188:191], v194 offset:49152
	ds_read_b128 v[196:199], v194 offset:50176
	ds_read_b128 v[200:203], v194 offset:51200
	ds_read_b128 v[206:209], v194 offset:52224
	ds_read_b128 v[210:213], v194 offset:53248
	ds_read_b128 v[214:217], v194 offset:54272
	ds_read_b128 v[218:221], v194 offset:55296
	ds_read_b128 v[222:225], v194 offset:56320
	global_load_lds_dwordx4 v[192:193], off
	s_add_i32 m0, s33, 0x2000
	s_add_u32 s44, s44, 0x80080
	v_lshl_add_u64 v[192:193], v[226:227], 0, s[92:93]
	s_addc_u32 s45, s45, 0
	s_add_i32 s33, s50, s61
	global_load_lds_dwordx4 v[192:193], off
	v_lshl_add_u64 v[192:193], s[44:45], 0, v[146:147]
	s_mov_b32 m0, s33
	s_nop 0
	global_load_lds_dwordx4 v146, s[44:45]
	v_lshl_add_u64 v[192:193], s[44:45], 0, v[150:151]
	s_add_i32 m0, s33, 0x2000
	s_nop 0
	global_load_lds_dwordx4 v150, s[44:45]
	v_lshl_add_u64 v[192:193], v[228:229], 0, s[92:93]
	s_mov_b32 m0, s68
	s_nop 0
	global_load_lds_dwordx4 v[192:193], off
	v_lshl_add_u64 v[192:193], v[230:231], 0, s[92:93]
	s_mov_b32 m0, s69
	s_nop 0
	global_load_lds_dwordx4 v[192:193], off
	s_waitcnt vmcnt(8)
	s_waitcnt lgkmcnt(0)
	s_barrier
	s_setprio 1
	s_waitcnt lgkmcnt(0)
	v_mfma_f32_16x16x32_bf16 v[34:37], v[134:137], v[188:191], v[34:37]
	v_mfma_f32_16x16x32_bf16 v[34:37], v[138:141], v[196:199], v[34:37]
	v_mfma_f32_16x16x32_bf16 v[30:33], v[168:171], v[196:199], v[30:33]
	v_mfma_f32_16x16x32_bf16 v[30:33], v[142:145], v[188:191], v[30:33]
	v_mfma_f32_16x16x32_bf16 v[22:25], v[142:145], v[200:203], v[22:25]
	v_mfma_f32_16x16x32_bf16 v[22:25], v[168:171], v[206:209], v[22:25]
	v_mfma_f32_16x16x32_bf16 v[26:29], v[138:141], v[206:209], v[26:29]
	v_mfma_f32_16x16x32_bf16 v[26:29], v[134:137], v[200:203], v[26:29]
	v_mfma_f32_16x16x32_bf16 v[18:21], v[134:137], v[210:213], v[18:21]
	v_mfma_f32_16x16x32_bf16 v[18:21], v[138:141], v[214:217], v[18:21]
	v_mfma_f32_16x16x32_bf16 v[10:13], v[168:171], v[214:217], v[10:13]
	v_mfma_f32_16x16x32_bf16 v[10:13], v[142:145], v[210:213], v[10:13]
	v_mfma_f32_16x16x32_bf16 v[2:5], v[142:145], v[218:221], v[2:5]
	v_mfma_f32_16x16x32_bf16 v[2:5], v[168:171], v[222:225], v[2:5]
	v_mfma_f32_16x16x32_bf16 v[6:9], v[138:141], v[222:225], v[6:9]
	v_mfma_f32_16x16x32_bf16 v[6:9], v[134:137], v[218:221], v[6:9]
	s_setprio 0
	s_setprio 1
	v_mfma_f32_16x16x32_bf16 v[98:101], v[172:175], v[188:191], v[98:101]
	v_mfma_f32_16x16x32_bf16 v[98:101], v[176:179], v[196:199], v[98:101]
	v_mfma_f32_16x16x32_bf16 v[94:97], v[184:187], v[196:199], v[94:97]
	v_mfma_f32_16x16x32_bf16 v[94:97], v[180:183], v[188:191], v[94:97]
	v_mfma_f32_16x16x32_bf16 v[86:89], v[180:183], v[200:203], v[86:89]
	v_mfma_f32_16x16x32_bf16 v[86:89], v[184:187], v[206:209], v[86:89]
	v_mfma_f32_16x16x32_bf16 v[90:93], v[176:179], v[206:209], v[90:93]
	v_mfma_f32_16x16x32_bf16 v[90:93], v[172:175], v[200:203], v[90:93]
	v_mfma_f32_16x16x32_bf16 v[82:85], v[172:175], v[210:213], v[82:85]
	v_mfma_f32_16x16x32_bf16 v[82:85], v[176:179], v[214:217], v[82:85]
	v_mfma_f32_16x16x32_bf16 v[78:81], v[184:187], v[214:217], v[78:81]
	v_mfma_f32_16x16x32_bf16 v[78:81], v[180:183], v[210:213], v[78:81]
	v_mfma_f32_16x16x32_bf16 v[66:69], v[180:183], v[218:221], v[66:69]
	v_mfma_f32_16x16x32_bf16 v[66:69], v[184:187], v[222:225], v[66:69]
	v_mfma_f32_16x16x32_bf16 v[70:73], v[176:179], v[222:225], v[70:73]
	v_mfma_f32_16x16x32_bf16 v[70:73], v[172:175], v[218:221], v[70:73]
	s_setprio 0
	s_barrier
	s_add_i32 s49, s49, 2
	s_add_u32 s43, s43, 0x100
	s_addc_u32 s48, s48, 0
	s_add_u32 s40, s40, 0x100
	s_addc_u32 s41, s41, 0
	s_cmp_gt_u32 s49, 29

; #define PG8_STAGE(bufoff, gbase, voff) do { _Pragma("unroll") for (int _i = 0; _i < 2; ++_i) \
;         __builtin_amdgcn_global_load_lds((const unsigned*)((const char*)(gbase) + (voff)[_i]), (PG8_LAS unsigned*)(lds + (bufoff) + ldsw + _i * 8192), 16, 0, 0); } while (0)
; #define PG8_LDA(dst, b, h) do { _Pragma("unroll") for (int m = 0; m < 4; ++m) _Pragma("unroll") for (int k = 0; k < 2; ++k) dst[m][k] = *(const PG8_LAS bf16x8*)(lds + PG8_SA(b, h) + aoff + m * 2048 + k * 1024); } while (0)
; #define PG8_LDB(dst, b, h) do { _Pragma("unroll") for (int n = 0; n < 2; ++n) _Pragma("unroll") for (int k = 0; k < 2; ++k) dst[n][k] = *(const PG8_LAS bf16x8*)(lds + PG8_SB(b, h) + boff + n * 2048 + k * 1024); } while (0)
; #define PG8_WAIT_V(n) asm volatile("s_waitcnt vmcnt(" #n ")" ::: "memory")
; #define PG8_WAIT_L(n) asm volatile("s_waitcnt lgkmcnt(" #n ")" ::: "memory")
; #define PG8_BAR __builtin_amdgcn_s_barrier()
; #define PG8_SCHED __builtin_amdgcn_sched_barrier(0)
; template <class Epi, class Sched, bool ALIGN_EPI = false, bool SP2 = false>
; __device__ __forceinline__ void gemm_phase(PG8_LAS unsigned char* lds, const Gemm g, const Sched& S, const Epi& E) {
;     ...
;         const bool has_next = S.next(ui + 1, nxt);
;         const char* nA = has_next ? (const char*)g.A + (size_t)nxt.pm * tstep : cA; const char* nB = has_next ? (const char*)g.Bt + (size_t)nxt.pn * tstep : cB;
;         for (int t = 0; t < nt; t += 2) {
;             const bool last = (t == nt - 2);
;             const char* a1 = cA + (size_t)(t + 1) * kstep;
;             const char* a2 = last ? nA : cA + (size_t)(t + 2) * kstep; const char* b2 = last ? nB : cB + (size_t)(t + 2) * kstep;
;             const char* a3 = a2 + kstep; const char* b3 = b2 + kstep;
;             if (last && has_next) S.a_ready(nxt);
;             if constexpr (Epi::MID) { if (t == nt / 2) E.mid(acc, cur, wr, wc, fr, fq); }
;             if constexpr (SP2) {
;             PG8_LDB(B0, 0, 0); PG8_LDB(B1, 0, 1); PG8_SCHED; PG8_LDA(At, 0, 0); PG8_STAGE(PG8_SA(1, 1), a1 + hstep, voffA);
;             PG8_WAIT_V(8); PG8_WAIT_L(0); PG8_BAR; PG8_MMA(0, 0, At, B0); PG8_MMA(0, 1, At, B1); PG8_BAR; PG8_SCHED;
;             PG8_LDA(At, 0, 1); PG8_STAGE(PG8_SB(0, 0), b2, voffB); PG8_STAGE(PG8_SB(0, 1), b2 + hstep, voffB); PG8_STAGE(PG8_SA(0, 0), a2, voffA);
.LBB0_1222:
	s_ashr_i32 s21, s20, 31
	s_lshl_b64 s[22:23], s[20:21], 20
	s_add_u32 s22, s8, s22
	s_addc_u32 s23, s9, s23
	s_and_b64 s[24:25], s[2:3], exec
	s_cselect_b32 s5, s23, s29
	s_cselect_b32 s11, s22, s28
	s_ashr_i32 s19, s18, 31
	s_lshl_b64 s[24:25], s[18:19], 20
	s_add_u32 s24, s36, s24
	s_addc_u32 s25, s37, s25
	s_and_b64 s[30:31], s[2:3], exec
	s_cselect_b32 s19, s25, s27
	s_cselect_b32 s21, s24, s26
	s_add_u32 s54, s26, 0x100
	s_addc_u32 s55, s27, 0
	s_add_u32 s26, s28, 0x80080
	s_addc_u32 s27, s29, 0
	s_mov_b32 s56, -2
	s_add_u32 s28, s26, 0xfff80080
	s_addc_u32 s29, s27, -1
	s_add_i32 s33, 0, 0x10000
	s_cmp_eq_u32 s56, 28
	s_cselect_b32 s31, s5, s29
	s_cselect_b32 s30, s11, s28
	v_add_u32_e32 v161, s33, v155
	s_cselect_b32 s29, s19, s55
	s_cselect_b32 s28, s21, s54
	s_add_i32 s57, 0, 0x14000
	ds_read_b128 v[142:145], v161
	ds_read_b128 v[146:149], v161 offset:1024
	ds_read_b128 v[150:153], v161 offset:2048
	ds_read_b128 v[162:165], v161 offset:3072
	v_add_u32_e32 v161, s57, v155
	ds_read_b128 v[166:169], v161
	ds_read_b128 v[170:173], v161 offset:1024
	ds_read_b128 v[174:177], v161 offset:2048
	ds_read_b128 v[178:181], v161 offset:3072
	v_lshl_add_u64 v[202:203], s[26:27], 0, v[140:141]
	s_add_i32 m0, s42, 0xc000
	ds_read_b128 v[182:185], v160
	ds_read_b128 v[186:189], v160 offset:1024
	ds_read_b128 v[190:193], v160 offset:2048
	ds_read_b128 v[194:197], v160 offset:3072
	ds_read_b128 v[198:201], v160 offset:4096
	ds_read_b128 v[206:209], v160 offset:5120
	ds_read_b128 v[210:213], v160 offset:6144
	ds_read_b128 v[214:217], v160 offset:7168
	global_load_lds_dwordx4 v140, s[26:27]
	v_lshl_add_u64 v[202:203], s[26:27], 0, v[138:139]
	s_add_i32 m0, s42, 0xe000
	s_nop 0
	global_load_lds_dwordx4 v138, s[26:27]
	s_waitcnt vmcnt(8)
	s_waitcnt lgkmcnt(0)
	s_barrier
	s_setprio 1
	s_waitcnt lgkmcnt(0)
	v_mfma_f32_16x16x32_bf16 v[130:133], v[142:145], v[182:185], 0
	v_mfma_f32_16x16x32_bf16 v[130:133], v[146:149], v[186:189], v[130:133]
	v_mfma_f32_16x16x32_bf16 v[126:129], v[162:165], v[186:189], 0
	v_mfma_f32_16x16x32_bf16 v[126:129], v[150:153], v[182:185], v[126:129]
	v_mfma_f32_16x16x32_bf16 v[110:113], v[150:153], v[190:193], 0
	v_mfma_f32_16x16x32_bf16 v[110:113], v[162:165], v[194:197], v[110:113]
	v_mfma_f32_16x16x32_bf16 v[114:117], v[146:149], v[194:197], 0
	v_mfma_f32_16x16x32_bf16 v[114:117], v[142:145], v[190:193], v[114:117]
	v_mfma_f32_16x16x32_bf16 v[98:101], v[142:145], v[198:201], 0
	v_mfma_f32_16x16x32_bf16 v[98:101], v[146:149], v[206:209], v[98:101]
	v_mfma_f32_16x16x32_bf16 v[94:97], v[162:165], v[206:209], 0
	v_mfma_f32_16x16x32_bf16 v[94:97], v[150:153], v[198:201], v[94:97]
	v_mfma_f32_16x16x32_bf16 v[78:81], v[150:153], v[210:213], 0
	v_mfma_f32_16x16x32_bf16 v[78:81], v[162:165], v[214:217], v[78:81]
	v_mfma_f32_16x16x32_bf16 v[82:85], v[146:149], v[214:217], 0
	v_mfma_f32_16x16x32_bf16 v[82:85], v[142:145], v[210:213], v[82:85]
	s_setprio 0
	s_setprio 1
	v_mfma_f32_16x16x32_bf16 v[122:125], v[166:169], v[182:185], 0
	v_mfma_f32_16x16x32_bf16 v[122:125], v[170:173], v[186:189], v[122:125]
	v_mfma_f32_16x16x32_bf16 v[118:121], v[178:181], v[186:189], 0
	v_mfma_f32_16x16x32_bf16 v[118:121], v[174:177], v[182:185], v[118:121]
	v_mfma_f32_16x16x32_bf16 v[102:105], v[174:177], v[190:193], 0
	v_mfma_f32_16x16x32_bf16 v[102:105], v[178:181], v[194:197], v[102:105]
	v_mfma_f32_16x16x32_bf16 v[106:109], v[170:173], v[194:197], 0
	v_mfma_f32_16x16x32_bf16 v[106:109], v[166:169], v[190:193], v[106:109]
	v_mfma_f32_16x16x32_bf16 v[90:93], v[166:169], v[198:201], 0
	v_mfma_f32_16x16x32_bf16 v[90:93], v[170:173], v[206:209], v[90:93]
	v_mfma_f32_16x16x32_bf16 v[86:89], v[178:181], v[206:209], 0
	v_mfma_f32_16x16x32_bf16 v[86:89], v[174:177], v[198:201], v[86:89]
	v_mfma_f32_16x16x32_bf16 v[70:73], v[174:177], v[210:213], 0
	v_mfma_f32_16x16x32_bf16 v[70:73], v[178:181], v[214:217], v[70:73]
	v_mfma_f32_16x16x32_bf16 v[74:77], v[170:173], v[214:217], 0
	v_mfma_f32_16x16x32_bf16 v[74:77], v[166:169], v[210:213], v[74:77]
	s_setprio 0
	s_barrier
	s_add_i32 s33, s33, s40
	v_lshl_add_u64 v[202:203], s[28:29], 0, v[0:1]
	s_mov_b32 m0, s33
	ds_read_b128 v[182:185], v160 offset:16384
	ds_read_b128 v[186:189], v160 offset:17408
	ds_read_b128 v[190:193], v160 offset:18432
	ds_read_b128 v[194:197], v160 offset:19456
	ds_read_b128 v[198:201], v160 offset:20480
	ds_read_b128 v[206:209], v160 offset:21504
	ds_read_b128 v[210:213], v160 offset:22528
	ds_read_b128 v[214:217], v160 offset:23552
	global_load_lds_dwordx4 v0, s[28:29]
	s_add_i32 m0, s33, 0x2000
	s_add_u32 s58, s28, 0x80000
	v_lshl_add_u64 v[218:219], s[28:29], 0, v[14:15]
	s_addc_u32 s59, s29, 0
	s_add_i32 s33, s57, s40
	global_load_lds_dwordx4 v14, s[28:29]
	v_lshl_add_u64 v[220:221], s[58:59], 0, v[0:1]
	s_mov_b32 m0, s33
	v_lshl_add_u64 v[222:223], s[30:31], 0, v[134:135]
	global_load_lds_dwordx4 v0, s[58:59]
	v_lshl_add_u64 v[220:221], s[58:59], 0, v[14:15]
	s_add_i32 m0, s33, 0x2000
	s_nop 0
	global_load_lds_dwordx4 v14, s[58:59]
	v_lshl_add_u64 v[220:221], s[30:31], 0, v[136:137]
	s_mov_b32 m0, s42
	s_nop 0
	global_load_lds_dwordx4 v136, s[30:31]
	s_mov_b32 m0, s43
	s_nop 0
	global_load_lds_dwordx4 v134, s[30:31]
	s_waitcnt vmcnt(8)
	s_waitcnt lgkmcnt(0)
	s_barrier
; #define PG8_STAGE(bufoff, gbase, voff) do { _Pragma("unroll") for (int _i = 0; _i < 2; ++_i) \
;         __builtin_amdgcn_global_load_lds((const unsigned*)((const char*)(gbase) + (voff)[_i]), (PG8_LAS unsigned*)(lds + (bufoff) + ldsw + _i * 8192), 16, 0, 0); } while (0)
; #define PG8_LDA(dst, b, h) do { _Pragma("unroll") for (int m = 0; m < 4; ++m) _Pragma("unroll") for (int k = 0; k < 2; ++k) dst[m][k] = *(const PG8_LAS bf16x8*)(lds + PG8_SA(b, h) + aoff + m * 2048 + k * 1024); } while (0)
; #define PG8_LDB(dst, b, h) do { _Pragma("unroll") for (int n = 0; n < 2; ++n) _Pragma("unroll") for (int k = 0; k < 2; ++k) dst[n][k] = *(const PG8_LAS bf16x8*)(lds + PG8_SB(b, h) + boff + n * 2048 + k * 1024); } while (0)
; #define PG8_MMA(ai, bj, At, Bt) do { __builtin_amdgcn_s_setprio(1); _Pragma("unroll") for (int m = 0; m < 4; ++m) _Pragma("unroll") for (int n = 0; n < 2; ++n) _Pragma("unroll") for (int k = 0; k < 2; ++k) \
;         acc[ai][bj][m][n] = __builtin_amdgcn_mfma_f32_16x16x32_bf16(Bt[n][k], At[m][k], acc[ai][bj][m][n], 0, 0, 0); __builtin_amdgcn_s_setprio(0); } while (0)
; #define PG8_WAIT_V(n) asm volatile("s_waitcnt vmcnt(" #n ")" ::: "memory")
; #define PG8_WAIT_L(n) asm volatile("s_waitcnt lgkmcnt(" #n ")" ::: "memory")
; #define PG8_BAR __builtin_amdgcn_s_barrier()
; #define PG8_SCHED __builtin_amdgcn_sched_barrier(0)
; template <class Epi, class Sched, bool ALIGN_EPI = false, bool SP2 = false>
; __device__ __forceinline__ void gemm_phase(PG8_LAS unsigned char* lds, const Gemm g, const Sched& S, const Epi& E) {
;     ...
;             PG8_WAIT_V(8); PG8_WAIT_L(0); PG8_BAR; PG8_MMA(1, 0, At, B0); PG8_MMA(1, 1, At, B1); PG8_BAR; PG8_SCHED;
;             PG8_LDB(B0, 1, 0); PG8_LDB(B1, 1, 1); PG8_SCHED; PG8_LDA(At, 1, 0); PG8_STAGE(PG8_SA(0, 1), a2 + hstep, voffA);
;             PG8_WAIT_V(8); PG8_WAIT_L(0); PG8_BAR; PG8_MMA(0, 0, At, B0); PG8_MMA(0, 1, At, B1); PG8_BAR; PG8_SCHED;
	s_setprio 1
	s_waitcnt lgkmcnt(0)
	v_mfma_f32_16x16x32_bf16 v[66:69], v[142:145], v[182:185], 0
	v_mfma_f32_16x16x32_bf16 v[66:69], v[146:149], v[186:189], v[66:69]
	v_mfma_f32_16x16x32_bf16 v[62:65], v[162:165], v[186:189], 0
	v_mfma_f32_16x16x32_bf16 v[62:65], v[150:153], v[182:185], v[62:65]
	v_mfma_f32_16x16x32_bf16 v[46:49], v[150:153], v[190:193], 0
	v_mfma_f32_16x16x32_bf16 v[46:49], v[162:165], v[194:197], v[46:49]
	v_mfma_f32_16x16x32_bf16 v[50:53], v[146:149], v[194:197], 0
	v_mfma_f32_16x16x32_bf16 v[50:53], v[142:145], v[190:193], v[50:53]
	v_mfma_f32_16x16x32_bf16 v[34:37], v[142:145], v[198:201], 0
	v_mfma_f32_16x16x32_bf16 v[34:37], v[146:149], v[206:209], v[34:37]
	v_mfma_f32_16x16x32_bf16 v[30:33], v[162:165], v[206:209], 0
	v_mfma_f32_16x16x32_bf16 v[30:33], v[150:153], v[198:201], v[30:33]
	v_mfma_f32_16x16x32_bf16 v[10:13], v[150:153], v[210:213], 0
	v_mfma_f32_16x16x32_bf16 v[10:13], v[162:165], v[214:217], v[10:13]
	v_mfma_f32_16x16x32_bf16 v[18:21], v[146:149], v[214:217], 0
	v_mfma_f32_16x16x32_bf16 v[18:21], v[142:145], v[210:213], v[18:21]
	s_setprio 0
	s_setprio 1
	v_mfma_f32_16x16x32_bf16 v[58:61], v[166:169], v[182:185], 0
	v_mfma_f32_16x16x32_bf16 v[58:61], v[170:173], v[186:189], v[58:61]
	v_mfma_f32_16x16x32_bf16 v[54:57], v[178:181], v[186:189], 0
	v_mfma_f32_16x16x32_bf16 v[54:57], v[174:177], v[182:185], v[54:57]
	v_mfma_f32_16x16x32_bf16 v[38:41], v[174:177], v[190:193], 0
	v_mfma_f32_16x16x32_bf16 v[38:41], v[178:181], v[194:197], v[38:41]
	v_mfma_f32_16x16x32_bf16 v[42:45], v[170:173], v[194:197], 0
	v_mfma_f32_16x16x32_bf16 v[42:45], v[166:169], v[190:193], v[42:45]
	v_mfma_f32_16x16x32_bf16 v[26:29], v[166:169], v[198:201], 0
	v_mfma_f32_16x16x32_bf16 v[26:29], v[170:173], v[206:209], v[26:29]
	v_mfma_f32_16x16x32_bf16 v[22:25], v[178:181], v[206:209], 0
	v_mfma_f32_16x16x32_bf16 v[22:25], v[174:177], v[198:201], v[22:25]
	v_mfma_f32_16x16x32_bf16 v[2:5], v[174:177], v[210:213], 0
	v_mfma_f32_16x16x32_bf16 v[2:5], v[178:181], v[214:217], v[2:5]
	v_mfma_f32_16x16x32_bf16 v[6:9], v[170:173], v[214:217], 0
	v_mfma_f32_16x16x32_bf16 v[6:9], v[166:169], v[210:213], v[6:9]
	s_setprio 0
	s_barrier
	s_add_i32 s33, 0, 0x18000
	v_add_u32_e32 v161, s33, v155
	s_add_i32 s57, 0, 0x1c000
	ds_read_b128 v[142:145], v161
	ds_read_b128 v[146:149], v161 offset:1024
	ds_read_b128 v[150:153], v161 offset:2048
	ds_read_b128 v[162:165], v161 offset:3072
	v_add_u32_e32 v161, s57, v155
	ds_read_b128 v[166:169], v161
	ds_read_b128 v[170:173], v161 offset:1024
	ds_read_b128 v[174:177], v161 offset:2048
	ds_read_b128 v[178:181], v161 offset:3072
	s_add_u32 s30, s30, 0x80000
	s_addc_u32 s31, s31, 0
	s_mov_b32 m0, s44
	v_lshl_add_u64 v[224:225], s[30:31], 0, v[136:137]
	ds_read_b128 v[182:185], v160 offset:32768
	ds_read_b128 v[186:189], v160 offset:33792
	ds_read_b128 v[190:193], v160 offset:34816
	ds_read_b128 v[194:197], v160 offset:35840
	ds_read_b128 v[198:201], v160 offset:36864
	ds_read_b128 v[206:209], v160 offset:37888
	ds_read_b128 v[210:213], v160 offset:38912
	ds_read_b128 v[214:217], v160 offset:39936
	global_load_lds_dwordx4 v136, s[30:31]
	v_lshl_add_u64 v[224:225], s[30:31], 0, v[134:135]
	s_mov_b32 m0, s45
	s_nop 0
	global_load_lds_dwordx4 v134, s[30:31]
	s_waitcnt vmcnt(8)
	s_waitcnt lgkmcnt(0)
	s_barrier
	s_setprio 1
	s_waitcnt lgkmcnt(0)
	v_mfma_f32_16x16x32_bf16 v[130:133], v[142:145], v[182:185], v[130:133]
	v_mfma_f32_16x16x32_bf16 v[130:133], v[146:149], v[186:189], v[130:133]
	v_mfma_f32_16x16x32_bf16 v[126:129], v[162:165], v[186:189], v[126:129]
	v_mfma_f32_16x16x32_bf16 v[126:129], v[150:153], v[182:185], v[126:129]
	v_mfma_f32_16x16x32_bf16 v[110:113], v[150:153], v[190:193], v[110:113]
	v_mfma_f32_16x16x32_bf16 v[110:113], v[162:165], v[194:197], v[110:113]
	v_mfma_f32_16x16x32_bf16 v[114:117], v[146:149], v[194:197], v[114:117]
	v_mfma_f32_16x16x32_bf16 v[114:117], v[142:145], v[190:193], v[114:117]
	v_mfma_f32_16x16x32_bf16 v[98:101], v[142:145], v[198:201], v[98:101]
	v_mfma_f32_16x16x32_bf16 v[98:101], v[146:149], v[206:209], v[98:101]
	v_mfma_f32_16x16x32_bf16 v[94:97], v[162:165], v[206:209], v[94:97]
	v_mfma_f32_16x16x32_bf16 v[94:97], v[150:153], v[198:201], v[94:97]
	v_mfma_f32_16x16x32_bf16 v[78:81], v[150:153], v[210:213], v[78:81]
	v_mfma_f32_16x16x32_bf16 v[78:81], v[162:165], v[214:217], v[78:81]
	v_mfma_f32_16x16x32_bf16 v[82:85], v[146:149], v[214:217], v[82:85]
	v_mfma_f32_16x16x32_bf16 v[82:85], v[142:145], v[210:213], v[82:85]
	s_setprio 0
	s_setprio 1
	v_mfma_f32_16x16x32_bf16 v[122:125], v[166:169], v[182:185], v[122:125]
	v_mfma_f32_16x16x32_bf16 v[122:125], v[170:173], v[186:189], v[122:125]
	v_mfma_f32_16x16x32_bf16 v[118:121], v[178:181], v[186:189], v[118:121]
	v_mfma_f32_16x16x32_bf16 v[118:121], v[174:177], v[182:185], v[118:121]
	v_mfma_f32_16x16x32_bf16 v[102:105], v[174:177], v[190:193], v[102:105]
	v_mfma_f32_16x16x32_bf16 v[102:105], v[178:181], v[194:197], v[102:105]
	v_mfma_f32_16x16x32_bf16 v[106:109], v[170:173], v[194:197], v[106:109]
	v_mfma_f32_16x16x32_bf16 v[106:109], v[166:169], v[190:193], v[106:109]
	v_mfma_f32_16x16x32_bf16 v[90:93], v[166:169], v[198:201], v[90:93]
	v_mfma_f32_16x16x32_bf16 v[90:93], v[170:173], v[206:209], v[90:93]
	v_mfma_f32_16x16x32_bf16 v[86:89], v[178:181], v[206:209], v[86:89]
	v_mfma_f32_16x16x32_bf16 v[86:89], v[174:177], v[198:201], v[86:89]
	v_mfma_f32_16x16x32_bf16 v[70:73], v[174:177], v[210:213], v[70:73]
	v_mfma_f32_16x16x32_bf16 v[70:73], v[178:181], v[214:217], v[70:73]
	v_mfma_f32_16x16x32_bf16 v[74:77], v[170:173], v[214:217], v[74:77]
	v_mfma_f32_16x16x32_bf16 v[74:77], v[166:169], v[210:213], v[74:77]
	s_setprio 0
	s_barrier
; #define PG8_STAGE(bufoff, gbase, voff) do { _Pragma("unroll") for (int _i = 0; _i < 2; ++_i) \
;         __builtin_amdgcn_global_load_lds((const unsigned*)((const char*)(gbase) + (voff)[_i]), (PG8_LAS unsigned*)(lds + (bufoff) + ldsw + _i * 8192), 16, 0, 0); } while (0)
; #define PG8_LDA(dst, b, h) do { _Pragma("unroll") for (int m = 0; m < 4; ++m) _Pragma("unroll") for (int k = 0; k < 2; ++k) dst[m][k] = *(const PG8_LAS bf16x8*)(lds + PG8_SA(b, h) + aoff + m * 2048 + k * 1024); } while (0)
; #define PG8_MMA(ai, bj, At, Bt) do { __builtin_amdgcn_s_setprio(1); _Pragma("unroll") for (int m = 0; m < 4; ++m) _Pragma("unroll") for (int n = 0; n < 2; ++n) _Pragma("unroll") for (int k = 0; k < 2; ++k) \
;         acc[ai][bj][m][n] = __builtin_amdgcn_mfma_f32_16x16x32_bf16(Bt[n][k], At[m][k], acc[ai][bj][m][n], 0, 0, 0); __builtin_amdgcn_s_setprio(0); } while (0)
; #define PG8_WAIT_V(n) asm volatile("s_waitcnt vmcnt(" #n ")" ::: "memory")
; #define PG8_WAIT_L(n) asm volatile("s_waitcnt lgkmcnt(" #n ")" ::: "memory")
; #define PG8_BAR __builtin_amdgcn_s_barrier()
; #define PG8_SCHED __builtin_amdgcn_sched_barrier(0)
; template <class Epi, class Sched, bool ALIGN_EPI = false, bool SP2 = false>
; __device__ __forceinline__ void gemm_phase(PG8_LAS unsigned char* lds, const Gemm g, const Sched& S, const Epi& E) {
;     ...
;         for (int t = 0; t < nt; t += 2) {
;             const bool last = (t == nt - 2);
;             const char* a1 = cA + (size_t)(t + 1) * kstep;
;             const char* a2 = last ? nA : cA + (size_t)(t + 2) * kstep; const char* b2 = last ? nB : cB + (size_t)(t + 2) * kstep;
;     ...
;             PG8_LDA(At, 1, 1); PG8_STAGE(PG8_SB(1, 0), b3, voffB); PG8_STAGE(PG8_SB(1, 1), b3 + hstep, voffB); PG8_STAGE(PG8_SA(1, 0), a3, voffA);
;             PG8_WAIT_V(8); PG8_WAIT_L(0); PG8_BAR; PG8_MMA(1, 0, At, B0); PG8_MMA(1, 1, At, B1); PG8_BAR; PG8_SCHED;
	s_add_i32 s30, s33, s40
	v_lshl_add_u64 v[202:203], v[202:203], 0, s[92:93]
	s_mov_b32 m0, s30
	ds_read_b128 v[182:185], v160 offset:49152
	ds_read_b128 v[186:189], v160 offset:50176
	ds_read_b128 v[190:193], v160 offset:51200
	ds_read_b128 v[194:197], v160 offset:52224
	ds_read_b128 v[198:201], v160 offset:53248
	ds_read_b128 v[206:209], v160 offset:54272
	ds_read_b128 v[210:213], v160 offset:55296
	ds_read_b128 v[214:217], v160 offset:56320
	global_load_lds_dwordx4 v[202:203], off
	s_add_i32 m0, s30, 0x2000
	s_add_u32 s28, s28, 0x80080
	v_lshl_add_u64 v[202:203], v[218:219], 0, s[92:93]
	s_addc_u32 s29, s29, 0
	s_add_i32 s30, s57, s40
	global_load_lds_dwordx4 v[202:203], off
	v_lshl_add_u64 v[202:203], s[28:29], 0, v[0:1]
	s_mov_b32 m0, s30
	s_nop 0
	global_load_lds_dwordx4 v0, s[28:29]
	v_lshl_add_u64 v[202:203], s[28:29], 0, v[14:15]
	s_add_i32 m0, s30, 0x2000
	s_nop 0
	global_load_lds_dwordx4 v14, s[28:29]
	v_lshl_add_u64 v[202:203], v[220:221], 0, s[92:93]
	s_mov_b32 m0, s47
	s_nop 0
	global_load_lds_dwordx4 v[202:203], off
	v_lshl_add_u64 v[202:203], v[222:223], 0, s[92:93]
	s_mov_b32 m0, s48
	s_nop 0
	global_load_lds_dwordx4 v[202:203], off
	s_waitcnt vmcnt(8)
	s_waitcnt lgkmcnt(0)
	s_barrier
	s_setprio 1
	s_waitcnt lgkmcnt(0)
	v_mfma_f32_16x16x32_bf16 v[66:69], v[142:145], v[182:185], v[66:69]
	v_mfma_f32_16x16x32_bf16 v[66:69], v[146:149], v[186:189], v[66:69]
	v_mfma_f32_16x16x32_bf16 v[62:65], v[162:165], v[186:189], v[62:65]
	v_mfma_f32_16x16x32_bf16 v[62:65], v[150:153], v[182:185], v[62:65]
	v_mfma_f32_16x16x32_bf16 v[46:49], v[150:153], v[190:193], v[46:49]
	v_mfma_f32_16x16x32_bf16 v[46:49], v[162:165], v[194:197], v[46:49]
	v_mfma_f32_16x16x32_bf16 v[50:53], v[146:149], v[194:197], v[50:53]
	v_mfma_f32_16x16x32_bf16 v[50:53], v[142:145], v[190:193], v[50:53]
	v_mfma_f32_16x16x32_bf16 v[34:37], v[142:145], v[198:201], v[34:37]
	v_mfma_f32_16x16x32_bf16 v[34:37], v[146:149], v[206:209], v[34:37]
	v_mfma_f32_16x16x32_bf16 v[30:33], v[162:165], v[206:209], v[30:33]
	v_mfma_f32_16x16x32_bf16 v[30:33], v[150:153], v[198:201], v[30:33]
	v_mfma_f32_16x16x32_bf16 v[10:13], v[150:153], v[210:213], v[10:13]
	v_mfma_f32_16x16x32_bf16 v[10:13], v[162:165], v[214:217], v[10:13]
	v_mfma_f32_16x16x32_bf16 v[18:21], v[146:149], v[214:217], v[18:21]
	v_mfma_f32_16x16x32_bf16 v[18:21], v[142:145], v[210:213], v[18:21]
	s_setprio 0
	s_setprio 1
	v_mfma_f32_16x16x32_bf16 v[58:61], v[166:169], v[182:185], v[58:61]
	v_mfma_f32_16x16x32_bf16 v[58:61], v[170:173], v[186:189], v[58:61]
	v_mfma_f32_16x16x32_bf16 v[54:57], v[178:181], v[186:189], v[54:57]
	v_mfma_f32_16x16x32_bf16 v[54:57], v[174:177], v[182:185], v[54:57]
	v_mfma_f32_16x16x32_bf16 v[38:41], v[174:177], v[190:193], v[38:41]
	v_mfma_f32_16x16x32_bf16 v[38:41], v[178:181], v[194:197], v[38:41]
	v_mfma_f32_16x16x32_bf16 v[42:45], v[170:173], v[194:197], v[42:45]
	v_mfma_f32_16x16x32_bf16 v[42:45], v[166:169], v[190:193], v[42:45]
	v_mfma_f32_16x16x32_bf16 v[26:29], v[166:169], v[198:201], v[26:29]
	v_mfma_f32_16x16x32_bf16 v[26:29], v[170:173], v[206:209], v[26:29]
	v_mfma_f32_16x16x32_bf16 v[22:25], v[178:181], v[206:209], v[22:25]
	v_mfma_f32_16x16x32_bf16 v[22:25], v[174:177], v[198:201], v[22:25]
	v_mfma_f32_16x16x32_bf16 v[2:5], v[174:177], v[210:213], v[2:5]
	v_mfma_f32_16x16x32_bf16 v[2:5], v[178:181], v[214:217], v[2:5]
	v_mfma_f32_16x16x32_bf16 v[6:9], v[170:173], v[214:217], v[6:9]
	v_mfma_f32_16x16x32_bf16 v[6:9], v[166:169], v[210:213], v[6:9]
	s_setprio 0
	s_barrier
	s_add_i32 s56, s56, 2
	s_add_u32 s54, s54, 0x100
	s_addc_u32 s55, s55, 0
	s_add_u32 s26, s26, 0x100
	s_addc_u32 s27, s27, 0
	s_cmp_gt_u32 s56, 29

; #define PG8_STAGE(bufoff, gbase, voff) do { _Pragma("unroll") for (int _i = 0; _i < 2; ++_i) \
;         __builtin_amdgcn_global_load_lds((const unsigned*)((const char*)(gbase) + (voff)[_i]), (PG8_LAS unsigned*)(lds + (bufoff) + ldsw + _i * 8192), 16, 0, 0); } while (0)
; #define PG8_LDA(dst, b, h) do { _Pragma("unroll") for (int m = 0; m < 4; ++m) _Pragma("unroll") for (int k = 0; k < 2; ++k) dst[m][k] = *(const PG8_LAS bf16x8*)(lds + PG8_SA(b, h) + aoff + m * 2048 + k * 1024); } while (0)
; #define PG8_LDB(dst, b, h) do { _Pragma("unroll") for (int n = 0; n < 2; ++n) _Pragma("unroll") for (int k = 0; k < 2; ++k) dst[n][k] = *(const PG8_LAS bf16x8*)(lds + PG8_SB(b, h) + boff + n * 2048 + k * 1024); } while (0)
; #define PG8_MMA(ai, bj, At, Bt) do { __builtin_amdgcn_s_setprio(1); _Pragma("unroll") for (int m = 0; m < 4; ++m) _Pragma("unroll") for (int n = 0; n < 2; ++n) _Pragma("unroll") for (int k = 0; k < 2; ++k) \
;         acc[ai][bj][m][n] = __builtin_amdgcn_mfma_f32_16x16x32_bf16(Bt[n][k], At[m][k], acc[ai][bj][m][n], 0, 0, 0); __builtin_amdgcn_s_setprio(0); } while (0)
; #define PG8_WAIT_V(n) asm volatile("s_waitcnt vmcnt(" #n ")" ::: "memory")
; #define PG8_WAIT_L(n) asm volatile("s_waitcnt lgkmcnt(" #n ")" ::: "memory")
; #define PG8_BAR __builtin_amdgcn_s_barrier()
; #define PG8_SCHED __builtin_amdgcn_sched_barrier(0)
; template <class Epi, class Sched, bool ALIGN_EPI = false, bool SP2 = false>
; __device__ __forceinline__ void gemm_phase(PG8_LAS unsigned char* lds, const Gemm g, const Sched& S, const Epi& E) {
;     ...
;             PG8_LDB(B0, 0, 0); PG8_LDB(B1, 0, 1); PG8_SCHED; PG8_LDA(At, 0, 0); PG8_STAGE(PG8_SA(1, 1), a1 + hstep, voffA);
;             PG8_WAIT_V(8); PG8_WAIT_L(0); PG8_BAR; PG8_MMA(0, 0, At, B0); PG8_MMA(0, 1, At, B1); PG8_BAR; PG8_SCHED;
;             PG8_LDA(At, 0, 1); PG8_STAGE(PG8_SB(0, 0), b2, voffB); PG8_STAGE(PG8_SB(0, 1), b2 + hstep, voffB); PG8_STAGE(PG8_SA(0, 0), a2, voffA);
;             PG8_WAIT_V(8); PG8_WAIT_L(0); PG8_BAR; PG8_MMA(1, 0, At, B0); PG8_MMA(1, 1, At, B1); PG8_BAR; PG8_SCHED;
;     ...
; #pragma unroll
;         for (int a = 0; a < 2; ++a)
; #pragma unroll
;             for (int b = 0; b < 2; ++b)
; #pragma unroll
;                 for (int m = 0; m < 4; ++m)
; #pragma unroll
;                     for (int n = 0; n < 2; ++n) acc[a][b][m][n] = (f32x4){0.f, 0.f, 0.f, 0.f};
.LBB0_1328:
	s_add_u32 s51, s26, 0x100
	s_addc_u32 s52, s27, 0
	s_mov_b32 s53, -2
	s_add_u32 s4, s24, 0x100
	s_addc_u32 s5, s25, 0
	s_add_i32 s33, 0, 0x10000
	s_cmpk_eq_i32 s53, 0x54
	s_cselect_b32 s29, s21, s5
	s_cselect_b32 s28, s20, s4
	s_cselect_b32 s27, s23, s52
	s_cselect_b32 s26, s22, s51
	s_add_i32 s54, 0, 0x14000
	v_add_u32_e32 v98, s33, v199
	v_add_u32_e32 v146, s54, v199
	ds_read_b128 v[70:73], v98
	ds_read_b128 v[74:77], v98 offset:1024
	ds_read_b128 v[86:89], v98 offset:2048
	ds_read_b128 v[98:101], v98 offset:3072
	ds_read_b128 v[110:113], v146
	ds_read_b128 v[122:125], v146 offset:1024
	ds_read_b128 v[134:137], v146 offset:2048
	ds_read_b128 v[146:149], v146 offset:3072
	v_lshl_add_u64 v[202:203], s[24:25], 0, v[208:209]
	s_add_i32 m0, s39, 0xc000
	ds_read_b128 v[158:161], v201
	ds_read_b128 v[162:165], v201 offset:1024
	ds_read_b128 v[174:177], v201 offset:2048
	ds_read_b128 v[178:181], v201 offset:3072
	ds_read_b128 v[182:185], v201 offset:4096
	ds_read_b128 v[186:189], v201 offset:5120
	ds_read_b128 v[190:193], v201 offset:6144
	ds_read_b128 v[210:213], v201 offset:7168
	global_load_lds_dwordx4 v208, s[24:25]
	v_lshl_add_u64 v[202:203], s[24:25], 0, v[206:207]
	s_add_i32 m0, s39, 0xe000
	s_nop 0
	global_load_lds_dwordx4 v206, s[24:25]
	s_waitcnt vmcnt(8)
	s_waitcnt lgkmcnt(0)
	s_barrier
	s_setprio 1
	s_waitcnt lgkmcnt(0)
	v_mfma_f32_16x16x32_bf16 v[170:173], v[70:73], v[158:161], 0
	v_mfma_f32_16x16x32_bf16 v[170:173], v[74:77], v[162:165], v[170:173]
	v_mfma_f32_16x16x32_bf16 v[166:169], v[98:101], v[162:165], 0
	v_mfma_f32_16x16x32_bf16 v[166:169], v[86:89], v[158:161], v[166:169]
	v_mfma_f32_16x16x32_bf16 v[138:141], v[86:89], v[174:177], 0
	v_mfma_f32_16x16x32_bf16 v[138:141], v[98:101], v[178:181], v[138:141]
	v_mfma_f32_16x16x32_bf16 v[142:145], v[74:77], v[178:181], 0
	v_mfma_f32_16x16x32_bf16 v[142:145], v[70:73], v[174:177], v[142:145]
	v_mfma_f32_16x16x32_bf16 v[118:121], v[70:73], v[182:185], 0
	v_mfma_f32_16x16x32_bf16 v[118:121], v[74:77], v[186:189], v[118:121]
	v_mfma_f32_16x16x32_bf16 v[114:117], v[98:101], v[186:189], 0
	v_mfma_f32_16x16x32_bf16 v[114:117], v[86:89], v[182:185], v[114:117]
	v_mfma_f32_16x16x32_bf16 v[90:93], v[86:89], v[190:193], 0
	v_mfma_f32_16x16x32_bf16 v[90:93], v[98:101], v[210:213], v[90:93]
	v_mfma_f32_16x16x32_bf16 v[94:97], v[74:77], v[210:213], 0
	v_mfma_f32_16x16x32_bf16 v[94:97], v[70:73], v[190:193], v[94:97]
	s_setprio 0
	s_setprio 1
	v_mfma_f32_16x16x32_bf16 v[154:157], v[110:113], v[158:161], 0
	v_mfma_f32_16x16x32_bf16 v[154:157], v[122:125], v[162:165], v[154:157]
	v_mfma_f32_16x16x32_bf16 v[150:153], v[146:149], v[162:165], 0
	v_mfma_f32_16x16x32_bf16 v[150:153], v[134:137], v[158:161], v[150:153]
	v_mfma_f32_16x16x32_bf16 v[126:129], v[134:137], v[174:177], 0
	v_mfma_f32_16x16x32_bf16 v[126:129], v[146:149], v[178:181], v[126:129]
	v_mfma_f32_16x16x32_bf16 v[130:133], v[122:125], v[178:181], 0
	v_mfma_f32_16x16x32_bf16 v[130:133], v[110:113], v[174:177], v[130:133]
	v_mfma_f32_16x16x32_bf16 v[106:109], v[110:113], v[182:185], 0
	v_mfma_f32_16x16x32_bf16 v[106:109], v[122:125], v[186:189], v[106:109]
	v_mfma_f32_16x16x32_bf16 v[102:105], v[146:149], v[186:189], 0
	v_mfma_f32_16x16x32_bf16 v[102:105], v[134:137], v[182:185], v[102:105]
	v_mfma_f32_16x16x32_bf16 v[78:81], v[134:137], v[190:193], 0
	v_mfma_f32_16x16x32_bf16 v[78:81], v[146:149], v[210:213], v[78:81]
	v_mfma_f32_16x16x32_bf16 v[82:85], v[122:125], v[210:213], 0
	v_mfma_f32_16x16x32_bf16 v[82:85], v[110:113], v[190:193], v[82:85]
	s_setprio 0
	s_barrier
	s_add_i32 s24, s33, s38
	v_lshl_add_u64 v[202:203], s[26:27], 0, v[0:1]
	s_mov_b32 m0, s24
	ds_read_b128 v[158:161], v201 offset:16384
	ds_read_b128 v[162:165], v201 offset:17408
	ds_read_b128 v[174:177], v201 offset:18432
	ds_read_b128 v[178:181], v201 offset:19456
	ds_read_b128 v[182:185], v201 offset:20480
	ds_read_b128 v[186:189], v201 offset:21504
	ds_read_b128 v[190:193], v201 offset:22528
	ds_read_b128 v[210:213], v201 offset:23552
	global_load_lds_dwordx4 v0, s[26:27]
	s_add_i32 m0, s24, 0x2000
	s_add_u32 s24, s26, 0x160000
	v_lshl_add_u64 v[214:215], s[26:27], 0, v[196:197]
	s_addc_u32 s25, s27, 0
	s_add_i32 s33, s54, s38
	global_load_lds_dwordx4 v196, s[26:27]
	v_lshl_add_u64 v[216:217], s[24:25], 0, v[0:1]
	s_mov_b32 m0, s33
	v_lshl_add_u64 v[218:219], s[28:29], 0, v[194:195]
	global_load_lds_dwordx4 v0, s[24:25]
	v_lshl_add_u64 v[216:217], s[24:25], 0, v[196:197]
	s_add_i32 m0, s33, 0x2000
	s_nop 0
	global_load_lds_dwordx4 v196, s[24:25]
	v_lshl_add_u64 v[216:217], s[28:29], 0, v[14:15]
	s_mov_b32 m0, s39
	s_nop 0
	global_load_lds_dwordx4 v14, s[28:29]
	s_mov_b32 m0, s40
	s_nop 0
	global_load_lds_dwordx4 v194, s[28:29]
	s_waitcnt vmcnt(8)
	s_waitcnt lgkmcnt(0)
	s_barrier
; #define PG8_STAGE(bufoff, gbase, voff) do { _Pragma("unroll") for (int _i = 0; _i < 2; ++_i) \
;         __builtin_amdgcn_global_load_lds((const unsigned*)((const char*)(gbase) + (voff)[_i]), (PG8_LAS unsigned*)(lds + (bufoff) + ldsw + _i * 8192), 16, 0, 0); } while (0)
; #define PG8_LDA(dst, b, h) do { _Pragma("unroll") for (int m = 0; m < 4; ++m) _Pragma("unroll") for (int k = 0; k < 2; ++k) dst[m][k] = *(const PG8_LAS bf16x8*)(lds + PG8_SA(b, h) + aoff + m * 2048 + k * 1024); } while (0)
; #define PG8_LDB(dst, b, h) do { _Pragma("unroll") for (int n = 0; n < 2; ++n) _Pragma("unroll") for (int k = 0; k < 2; ++k) dst[n][k] = *(const PG8_LAS bf16x8*)(lds + PG8_SB(b, h) + boff + n * 2048 + k * 1024); } while (0)
; #define PG8_MMA(ai, bj, At, Bt) do { __builtin_amdgcn_s_setprio(1); _Pragma("unroll") for (int m = 0; m < 4; ++m) _Pragma("unroll") for (int n = 0; n < 2; ++n) _Pragma("unroll") for (int k = 0; k < 2; ++k) \
;         acc[ai][bj][m][n] = __builtin_amdgcn_mfma_f32_16x16x32_bf16(Bt[n][k], At[m][k], acc[ai][bj][m][n], 0, 0, 0); __builtin_amdgcn_s_setprio(0); } while (0)
; #define PG8_WAIT_V(n) asm volatile("s_waitcnt vmcnt(" #n ")" ::: "memory")
; #define PG8_WAIT_L(n) asm volatile("s_waitcnt lgkmcnt(" #n ")" ::: "memory")
; #define PG8_BAR __builtin_amdgcn_s_barrier()
; #define PG8_SCHED __builtin_amdgcn_sched_barrier(0)
; template <class Epi, class Sched, bool ALIGN_EPI = false, bool SP2 = false>
; __device__ __forceinline__ void gemm_phase(PG8_LAS unsigned char* lds, const Gemm g, const Sched& S, const Epi& E) {
;     ...
;             PG8_WAIT_V(8); PG8_WAIT_L(0); PG8_BAR; PG8_MMA(1, 0, At, B0); PG8_MMA(1, 1, At, B1); PG8_BAR; PG8_SCHED;
;             PG8_LDB(B0, 1, 0); PG8_LDB(B1, 1, 1); PG8_SCHED; PG8_LDA(At, 1, 0); PG8_STAGE(PG8_SA(0, 1), a2 + hstep, voffA);
;             PG8_WAIT_V(8); PG8_WAIT_L(0); PG8_BAR; PG8_MMA(0, 0, At, B0); PG8_MMA(0, 1, At, B1); PG8_BAR; PG8_SCHED;
	s_setprio 1
	s_waitcnt lgkmcnt(0)
	v_mfma_f32_16x16x32_bf16 v[66:69], v[70:73], v[158:161], 0
	v_mfma_f32_16x16x32_bf16 v[66:69], v[74:77], v[162:165], v[66:69]
	v_mfma_f32_16x16x32_bf16 v[62:65], v[98:101], v[162:165], 0
	v_mfma_f32_16x16x32_bf16 v[62:65], v[86:89], v[158:161], v[62:65]
	v_mfma_f32_16x16x32_bf16 v[46:49], v[86:89], v[174:177], 0
	v_mfma_f32_16x16x32_bf16 v[46:49], v[98:101], v[178:181], v[46:49]
	v_mfma_f32_16x16x32_bf16 v[50:53], v[74:77], v[178:181], 0
	v_mfma_f32_16x16x32_bf16 v[50:53], v[70:73], v[174:177], v[50:53]
	v_mfma_f32_16x16x32_bf16 v[34:37], v[70:73], v[182:185], 0
	v_mfma_f32_16x16x32_bf16 v[34:37], v[74:77], v[186:189], v[34:37]
	v_mfma_f32_16x16x32_bf16 v[30:33], v[98:101], v[186:189], 0
	v_mfma_f32_16x16x32_bf16 v[30:33], v[86:89], v[182:185], v[30:33]
	v_mfma_f32_16x16x32_bf16 v[10:13], v[86:89], v[190:193], 0
	v_mfma_f32_16x16x32_bf16 v[10:13], v[98:101], v[210:213], v[10:13]
	v_mfma_f32_16x16x32_bf16 v[18:21], v[74:77], v[210:213], 0
	v_mfma_f32_16x16x32_bf16 v[18:21], v[70:73], v[190:193], v[18:21]
	s_setprio 0
	s_setprio 1
	v_mfma_f32_16x16x32_bf16 v[58:61], v[110:113], v[158:161], 0
	v_mfma_f32_16x16x32_bf16 v[58:61], v[122:125], v[162:165], v[58:61]
	v_mfma_f32_16x16x32_bf16 v[54:57], v[146:149], v[162:165], 0
	v_mfma_f32_16x16x32_bf16 v[54:57], v[134:137], v[158:161], v[54:57]
	v_mfma_f32_16x16x32_bf16 v[38:41], v[134:137], v[174:177], 0
	v_mfma_f32_16x16x32_bf16 v[38:41], v[146:149], v[178:181], v[38:41]
	v_mfma_f32_16x16x32_bf16 v[42:45], v[122:125], v[178:181], 0
	v_mfma_f32_16x16x32_bf16 v[42:45], v[110:113], v[174:177], v[42:45]
	v_mfma_f32_16x16x32_bf16 v[26:29], v[110:113], v[182:185], 0
	v_mfma_f32_16x16x32_bf16 v[26:29], v[122:125], v[186:189], v[26:29]
	v_mfma_f32_16x16x32_bf16 v[22:25], v[146:149], v[186:189], 0
	v_mfma_f32_16x16x32_bf16 v[22:25], v[134:137], v[182:185], v[22:25]
	v_mfma_f32_16x16x32_bf16 v[2:5], v[134:137], v[190:193], 0
	v_mfma_f32_16x16x32_bf16 v[2:5], v[146:149], v[210:213], v[2:5]
	v_mfma_f32_16x16x32_bf16 v[6:9], v[122:125], v[210:213], 0
	v_mfma_f32_16x16x32_bf16 v[6:9], v[110:113], v[190:193], v[6:9]
	s_setprio 0
	s_barrier
	s_add_i32 s33, 0, 0x18000
	s_add_i32 s54, 0, 0x1c000
	v_add_u32_e32 v98, s33, v199
	v_add_u32_e32 v146, s54, v199
	ds_read_b128 v[70:73], v98
	ds_read_b128 v[74:77], v98 offset:1024
	ds_read_b128 v[86:89], v98 offset:2048
	ds_read_b128 v[98:101], v98 offset:3072
	ds_read_b128 v[110:113], v146
	ds_read_b128 v[122:125], v146 offset:1024
	ds_read_b128 v[134:137], v146 offset:2048
	ds_read_b128 v[146:149], v146 offset:3072
	s_add_u32 s24, s28, 0x160000
	s_addc_u32 s25, s29, 0
	s_mov_b32 m0, s41
	v_lshl_add_u64 v[220:221], s[24:25], 0, v[14:15]
	ds_read_b128 v[158:161], v201 offset:32768
	ds_read_b128 v[162:165], v201 offset:33792
	ds_read_b128 v[174:177], v201 offset:34816
	ds_read_b128 v[178:181], v201 offset:35840
	ds_read_b128 v[182:185], v201 offset:36864
	ds_read_b128 v[186:189], v201 offset:37888
	ds_read_b128 v[190:193], v201 offset:38912
	ds_read_b128 v[210:213], v201 offset:39936
	global_load_lds_dwordx4 v14, s[24:25]
	v_lshl_add_u64 v[220:221], s[24:25], 0, v[194:195]
	s_mov_b32 m0, s42
	s_nop 0
	global_load_lds_dwordx4 v194, s[24:25]
	s_waitcnt vmcnt(8)
	s_waitcnt lgkmcnt(0)
	s_barrier
	s_setprio 1
	s_waitcnt lgkmcnt(0)
	v_mfma_f32_16x16x32_bf16 v[170:173], v[70:73], v[158:161], v[170:173]
	v_mfma_f32_16x16x32_bf16 v[170:173], v[74:77], v[162:165], v[170:173]
	v_mfma_f32_16x16x32_bf16 v[166:169], v[98:101], v[162:165], v[166:169]
	v_mfma_f32_16x16x32_bf16 v[166:169], v[86:89], v[158:161], v[166:169]
	v_mfma_f32_16x16x32_bf16 v[138:141], v[86:89], v[174:177], v[138:141]
	v_mfma_f32_16x16x32_bf16 v[138:141], v[98:101], v[178:181], v[138:141]
	v_mfma_f32_16x16x32_bf16 v[142:145], v[74:77], v[178:181], v[142:145]
	v_mfma_f32_16x16x32_bf16 v[142:145], v[70:73], v[174:177], v[142:145]
	v_mfma_f32_16x16x32_bf16 v[118:121], v[70:73], v[182:185], v[118:121]
	v_mfma_f32_16x16x32_bf16 v[118:121], v[74:77], v[186:189], v[118:121]
	v_mfma_f32_16x16x32_bf16 v[114:117], v[98:101], v[186:189], v[114:117]
	v_mfma_f32_16x16x32_bf16 v[114:117], v[86:89], v[182:185], v[114:117]
	v_mfma_f32_16x16x32_bf16 v[90:93], v[86:89], v[190:193], v[90:93]
	v_mfma_f32_16x16x32_bf16 v[90:93], v[98:101], v[210:213], v[90:93]
	v_mfma_f32_16x16x32_bf16 v[94:97], v[74:77], v[210:213], v[94:97]
	v_mfma_f32_16x16x32_bf16 v[94:97], v[70:73], v[190:193], v[94:97]
	s_setprio 0
	s_setprio 1
	v_mfma_f32_16x16x32_bf16 v[154:157], v[110:113], v[158:161], v[154:157]
	v_mfma_f32_16x16x32_bf16 v[154:157], v[122:125], v[162:165], v[154:157]
	v_mfma_f32_16x16x32_bf16 v[150:153], v[146:149], v[162:165], v[150:153]
	v_mfma_f32_16x16x32_bf16 v[150:153], v[134:137], v[158:161], v[150:153]
	v_mfma_f32_16x16x32_bf16 v[126:129], v[134:137], v[174:177], v[126:129]
	v_mfma_f32_16x16x32_bf16 v[126:129], v[146:149], v[178:181], v[126:129]
	v_mfma_f32_16x16x32_bf16 v[130:133], v[122:125], v[178:181], v[130:133]
	v_mfma_f32_16x16x32_bf16 v[130:133], v[110:113], v[174:177], v[130:133]
	v_mfma_f32_16x16x32_bf16 v[106:109], v[110:113], v[182:185], v[106:109]
	v_mfma_f32_16x16x32_bf16 v[106:109], v[122:125], v[186:189], v[106:109]
	v_mfma_f32_16x16x32_bf16 v[102:105], v[146:149], v[186:189], v[102:105]
	v_mfma_f32_16x16x32_bf16 v[102:105], v[134:137], v[182:185], v[102:105]
	v_mfma_f32_16x16x32_bf16 v[78:81], v[134:137], v[190:193], v[78:81]
	v_mfma_f32_16x16x32_bf16 v[78:81], v[146:149], v[210:213], v[78:81]
	v_mfma_f32_16x16x32_bf16 v[82:85], v[122:125], v[210:213], v[82:85]
	v_mfma_f32_16x16x32_bf16 v[82:85], v[110:113], v[190:193], v[82:85]
	s_setprio 0
	s_barrier
; #define PG8_STAGE(bufoff, gbase, voff) do { _Pragma("unroll") for (int _i = 0; _i < 2; ++_i) \
;         __builtin_amdgcn_global_load_lds((const unsigned*)((const char*)(gbase) + (voff)[_i]), (PG8_LAS unsigned*)(lds + (bufoff) + ldsw + _i * 8192), 16, 0, 0); } while (0)
; #define PG8_LDA(dst, b, h) do { _Pragma("unroll") for (int m = 0; m < 4; ++m) _Pragma("unroll") for (int k = 0; k < 2; ++k) dst[m][k] = *(const PG8_LAS bf16x8*)(lds + PG8_SA(b, h) + aoff + m * 2048 + k * 1024); } while (0)
; #define PG8_MMA(ai, bj, At, Bt) do { __builtin_amdgcn_s_setprio(1); _Pragma("unroll") for (int m = 0; m < 4; ++m) _Pragma("unroll") for (int n = 0; n < 2; ++n) _Pragma("unroll") for (int k = 0; k < 2; ++k) \
;         acc[ai][bj][m][n] = __builtin_amdgcn_mfma_f32_16x16x32_bf16(Bt[n][k], At[m][k], acc[ai][bj][m][n], 0, 0, 0); __builtin_amdgcn_s_setprio(0); } while (0)
; #define PG8_WAIT_V(n) asm volatile("s_waitcnt vmcnt(" #n ")" ::: "memory")
; #define PG8_WAIT_L(n) asm volatile("s_waitcnt lgkmcnt(" #n ")" ::: "memory")
; #define PG8_BAR __builtin_amdgcn_s_barrier()
; #define PG8_SCHED __builtin_amdgcn_sched_barrier(0)
; template <class Epi, class Sched, bool ALIGN_EPI = false, bool SP2 = false>
; __device__ __forceinline__ void gemm_phase(PG8_LAS unsigned char* lds, const Gemm g, const Sched& S, const Epi& E) {
;     ...
;         for (int t = 0; t < nt; t += 2) {
;     ...
;             PG8_LDA(At, 1, 1); PG8_STAGE(PG8_SB(1, 0), b3, voffB); PG8_STAGE(PG8_SB(1, 1), b3 + hstep, voffB); PG8_STAGE(PG8_SA(1, 0), a3, voffA);
;             PG8_WAIT_V(8); PG8_WAIT_L(0); PG8_BAR; PG8_MMA(1, 0, At, B0); PG8_MMA(1, 1, At, B1); PG8_BAR; PG8_SCHED;
	s_add_i32 s24, s33, s38
	v_lshl_add_u64 v[202:203], v[202:203], 0, s[92:93]
	s_mov_b32 m0, s24
	ds_read_b128 v[158:161], v201 offset:49152
	ds_read_b128 v[162:165], v201 offset:50176
	ds_read_b128 v[174:177], v201 offset:51200
	ds_read_b128 v[178:181], v201 offset:52224
	ds_read_b128 v[182:185], v201 offset:53248
	ds_read_b128 v[186:189], v201 offset:54272
	ds_read_b128 v[190:193], v201 offset:55296
	ds_read_b128 v[210:213], v201 offset:56320
	global_load_lds_dwordx4 v[202:203], off
	s_add_i32 m0, s24, 0x2000
	s_add_u32 s24, s26, 0x160080
	v_lshl_add_u64 v[202:203], v[214:215], 0, s[92:93]
	s_addc_u32 s25, s27, 0
	s_add_i32 s26, s54, s38
	global_load_lds_dwordx4 v[202:203], off
	v_lshl_add_u64 v[202:203], s[24:25], 0, v[0:1]
	s_mov_b32 m0, s26
	s_nop 0
	global_load_lds_dwordx4 v0, s[24:25]
	v_lshl_add_u64 v[202:203], s[24:25], 0, v[196:197]
	s_add_i32 m0, s26, 0x2000
	s_nop 0
	global_load_lds_dwordx4 v196, s[24:25]
	v_lshl_add_u64 v[202:203], v[216:217], 0, s[92:93]
	s_mov_b32 m0, s44
	s_nop 0
	global_load_lds_dwordx4 v[202:203], off
	v_lshl_add_u64 v[202:203], v[218:219], 0, s[92:93]
	s_mov_b32 m0, s45
	s_nop 0
	global_load_lds_dwordx4 v[202:203], off
	s_waitcnt vmcnt(8)
	s_waitcnt lgkmcnt(0)
	s_barrier
	s_setprio 1
	s_waitcnt lgkmcnt(0)
	v_mfma_f32_16x16x32_bf16 v[66:69], v[70:73], v[158:161], v[66:69]
	v_mfma_f32_16x16x32_bf16 v[66:69], v[74:77], v[162:165], v[66:69]
	v_mfma_f32_16x16x32_bf16 v[62:65], v[98:101], v[162:165], v[62:65]
	v_mfma_f32_16x16x32_bf16 v[62:65], v[86:89], v[158:161], v[62:65]
	v_mfma_f32_16x16x32_bf16 v[46:49], v[86:89], v[174:177], v[46:49]
	v_mfma_f32_16x16x32_bf16 v[46:49], v[98:101], v[178:181], v[46:49]
	v_mfma_f32_16x16x32_bf16 v[50:53], v[74:77], v[178:181], v[50:53]
	v_mfma_f32_16x16x32_bf16 v[50:53], v[70:73], v[174:177], v[50:53]
	v_mfma_f32_16x16x32_bf16 v[34:37], v[70:73], v[182:185], v[34:37]
	v_mfma_f32_16x16x32_bf16 v[34:37], v[74:77], v[186:189], v[34:37]
	v_mfma_f32_16x16x32_bf16 v[30:33], v[98:101], v[186:189], v[30:33]
	v_mfma_f32_16x16x32_bf16 v[30:33], v[86:89], v[182:185], v[30:33]
	v_mfma_f32_16x16x32_bf16 v[10:13], v[86:89], v[190:193], v[10:13]
	v_mfma_f32_16x16x32_bf16 v[10:13], v[98:101], v[210:213], v[10:13]
	v_mfma_f32_16x16x32_bf16 v[18:21], v[74:77], v[210:213], v[18:21]
	v_mfma_f32_16x16x32_bf16 v[18:21], v[70:73], v[190:193], v[18:21]
	s_setprio 0
	s_setprio 1
	v_mfma_f32_16x16x32_bf16 v[58:61], v[110:113], v[158:161], v[58:61]
	v_mfma_f32_16x16x32_bf16 v[58:61], v[122:125], v[162:165], v[58:61]
	v_mfma_f32_16x16x32_bf16 v[54:57], v[146:149], v[162:165], v[54:57]
	v_mfma_f32_16x16x32_bf16 v[54:57], v[134:137], v[158:161], v[54:57]
	v_mfma_f32_16x16x32_bf16 v[38:41], v[134:137], v[174:177], v[38:41]
	v_mfma_f32_16x16x32_bf16 v[38:41], v[146:149], v[178:181], v[38:41]
	v_mfma_f32_16x16x32_bf16 v[42:45], v[122:125], v[178:181], v[42:45]
	v_mfma_f32_16x16x32_bf16 v[42:45], v[110:113], v[174:177], v[42:45]
	v_mfma_f32_16x16x32_bf16 v[26:29], v[110:113], v[182:185], v[26:29]
	v_mfma_f32_16x16x32_bf16 v[26:29], v[122:125], v[186:189], v[26:29]
	v_mfma_f32_16x16x32_bf16 v[22:25], v[146:149], v[186:189], v[22:25]
	v_mfma_f32_16x16x32_bf16 v[22:25], v[134:137], v[182:185], v[22:25]
	v_mfma_f32_16x16x32_bf16 v[2:5], v[134:137], v[190:193], v[2:5]
	v_mfma_f32_16x16x32_bf16 v[2:5], v[146:149], v[210:213], v[2:5]
	v_mfma_f32_16x16x32_bf16 v[6:9], v[122:125], v[210:213], v[6:9]
	v_mfma_f32_16x16x32_bf16 v[6:9], v[110:113], v[190:193], v[6:9]
	s_setprio 0
	s_barrier
	s_add_i32 s53, s53, 2
	s_add_u32 s51, s51, 0x100
	s_addc_u32 s52, s52, 0
	s_cmpk_gt_u32 s53, 0x55
	s_mov_b64 s[24:25], s[4:5]
